# first-iteration peel (no accumulator zeroing) in P2/P3/P7/P9 GEMM loops + redundant L1 invalidate dropped in the two panel-sum exchanges (sc1 loads)
# speedup vs baseline: 1.0387x; 1.0075x over previous
; #define PG8_STAGE(bufoff, gbase, voff) do { _Pragma("unroll") for (int _i = 0; _i < 2; ++_i) \
;         __builtin_amdgcn_global_load_lds((const unsigned*)((const char*)(gbase) + (voff)[_i]), (LAS unsigned*)(lds + (bufoff) + ldsw + _i * 8192), 16, 0, 0); } while (0)
; #define PG8_LDA(dst, b, h) do { _Pragma("unroll") for (int m = 0; m < 4; ++m) _Pragma("unroll") for (int k = 0; k < 2; ++k) dst[m][k] = *(const LAS bf16x8*)(lds + PG8_SA(b, h) + aoff + m * 2048 + k * 1024); } while (0)
; #define PG8_LDB(dst, b, h) do { _Pragma("unroll") for (int n = 0; n < 2; ++n) _Pragma("unroll") for (int k = 0; k < 2; ++k) dst[n][k] = *(const LAS bf16x8*)(lds + PG8_SB(b, h) + boff + n * 2048 + k * 1024); } while (0)
; #define PG8_MMA(ai, bj, At, Bt) do { __builtin_amdgcn_s_setprio(1); _Pragma("unroll") for (int m = 0; m < 4; ++m) _Pragma("unroll") for (int n = 0; n < 2; ++n) _Pragma("unroll") for (int k = 0; k < 2; ++k) \
;         acc[ai][bj][m][n] = __builtin_amdgcn_mfma_f32_16x16x32_bf16(Bt[n][k], At[m][k], acc[ai][bj][m][n], 0, 0, 0); __builtin_amdgcn_s_setprio(0); } while (0)
; #define PG8_WAIT_L(n) asm volatile("s_waitcnt lgkmcnt(" #n ")" ::: "memory")
; #define PG8_BAR __builtin_amdgcn_s_barrier()
; #define PG8_SCHED __builtin_amdgcn_sched_barrier(0)
; template <class Epi, class Sched>
; __device__ __forceinline__ void gemm_phase(LAS unsigned char* lds, const int K, const Sched& S, const Epi& E) {
;     ...
;             PG8_LDB(B0, 0, 0); PG8_SCHED; PG8_LDA(At, 0, 0); PG8_STAGE(PG8_SA(1, 1), a1 + hstepA, voffA);
;             PG8_WAIT_L(8); PG8_BAR; PG8_WAIT_L(0); PG8_MMA(0, 0, At, B0); PG8_BAR; PG8_SCHED;
;             PG8_LDB(B1, 0, 1); PG8_STAGE(PG8_SB(0, 0), b2, voffB);
;             PG8_BAR; PG8_WAIT_L(0); PG8_MMA(0, 1, At, B1); PG8_BAR;
;             PG8_LDA(At, 0, 1); PG8_STAGE(PG8_SA(0, 0), a2, voffA);
;             PG8_BAR; PG8_WAIT_L(0); PG8_MMA(1, 0, At, B0); PG8_BAR; PG8_SCHED;
;     ...
;                     for (int n = 0; n < 2; ++n) acc[a][b][m][n] = (f32x4){0.f, 0.f, 0.f, 0.f};
.LBB0_188:
	s_add_u32 s70, s70, 0x40080
	s_addc_u32 s71, s71, 0
	s_add_u32 s43, s72, 0x100
	s_addc_u32 s65, s73, 0
	s_mov_b32 s67, -2
	s_waitcnt lgkmcnt(0)
.Lpeel_p2:
	ds_read_b128 v[164:167], v160
	ds_read_b128 v[174:177], v160 offset:1024
	ds_read_b128 v[178:181], v160 offset:2048
	ds_read_b128 v[182:185], v160 offset:3072
	s_add_u32 s72, s70, 0xfffc0080
	s_addc_u32 s73, s71, -1
	s_cmp_eq_u32 s67, 12
	s_cselect_b32 s75, s45, s73
	s_cselect_b32 s74, s44, s72
	s_cselect_b32 s73, s47, s65
	s_cselect_b32 s72, s46, s43
	v_lshl_add_u64 v[168:169], s[70:71], 0, v[156:157]
	s_add_i32 m0, s55, 0xc000
	ds_read_b128 v[186:189], v161
	ds_read_b128 v[190:193], v161 offset:1024
	ds_read_b128 v[194:197], v161 offset:2048
	ds_read_b128 v[198:201], v161 offset:3072
	ds_read_b128 v[202:205], v161 offset:4096
	ds_read_b128 v[206:209], v161 offset:5120
	ds_read_b128 v[210:213], v161 offset:6144
	ds_read_b128 v[214:217], v161 offset:7168
	global_load_lds_dwordx4 v[168:169], off
	v_lshl_add_u64 v[168:169], s[70:71], 0, v[158:159]
	s_add_i32 m0, s55, 0xe000
	s_nop 0
	global_load_lds_dwordx4 v[168:169], off
	s_waitcnt lgkmcnt(8)
	s_barrier
	s_waitcnt lgkmcnt(0)
	s_setprio 1
	s_waitcnt lgkmcnt(0)
	v_mfma_f32_16x16x32_bf16 v[124:127], v[164:167], v[186:189], 0
	v_mfma_f32_16x16x32_bf16 v[120:123], v[178:181], v[186:189], 0
	v_mfma_f32_16x16x32_bf16 v[112:115], v[164:167], v[194:197], 0
	v_mfma_f32_16x16x32_bf16 v[104:107], v[178:181], v[194:197], 0
	v_mfma_f32_16x16x32_bf16 v[100:103], v[164:167], v[202:205], 0
	v_mfma_f32_16x16x32_bf16 v[92:95], v[178:181], v[202:205], 0
	v_mfma_f32_16x16x32_bf16 v[84:87], v[164:167], v[210:213], 0
	v_mfma_f32_16x16x32_bf16 v[76:79], v[178:181], v[210:213], 0
	v_mfma_f32_16x16x32_bf16 v[124:127], v[174:177], v[190:193], v[124:127]
	v_mfma_f32_16x16x32_bf16 v[120:123], v[182:185], v[190:193], v[120:123]
	v_mfma_f32_16x16x32_bf16 v[112:115], v[174:177], v[198:201], v[112:115]
	v_mfma_f32_16x16x32_bf16 v[104:107], v[182:185], v[198:201], v[104:107]
	v_mfma_f32_16x16x32_bf16 v[100:103], v[174:177], v[206:209], v[100:103]
	v_mfma_f32_16x16x32_bf16 v[92:95], v[182:185], v[206:209], v[92:95]
	v_mfma_f32_16x16x32_bf16 v[84:87], v[174:177], v[214:217], v[84:87]
	v_mfma_f32_16x16x32_bf16 v[76:79], v[182:185], v[214:217], v[76:79]
	s_setprio 0
	s_barrier
	s_add_i32 vcc_lo, s33, s54
	v_lshl_add_u64 v[168:169], s[72:73], 0, v[130:131]
	s_mov_b32 m0, vcc_lo
	ds_read_b128 v[218:221], v162
	ds_read_b128 v[222:225], v162 offset:1024
	ds_read_b128 v[226:229], v162 offset:2048
	ds_read_b128 v[230:233], v162 offset:3072
	global_load_lds_dwordx4 v[168:169], off
	v_lshl_add_u64 v[234:235], s[72:73], 0, v[134:135]
	s_add_i32 m0, vcc_lo, 0x2000
	s_nop 0
	global_load_lds_dwordx4 v[234:235], off
	s_barrier
	s_waitcnt lgkmcnt(0)
	s_setprio 1
	s_waitcnt lgkmcnt(0)
	v_mfma_f32_16x16x32_bf16 v[116:119], v[218:221], v[186:189], 0
	v_mfma_f32_16x16x32_bf16 v[108:111], v[226:229], v[186:189], 0
	v_mfma_f32_16x16x32_bf16 v[96:99], v[218:221], v[194:197], 0
	v_mfma_f32_16x16x32_bf16 v[88:91], v[226:229], v[194:197], 0
	v_mfma_f32_16x16x32_bf16 v[80:83], v[218:221], v[202:205], 0
	v_mfma_f32_16x16x32_bf16 v[72:75], v[226:229], v[202:205], 0
	v_mfma_f32_16x16x32_bf16 v[68:71], v[218:221], v[210:213], 0
	v_mfma_f32_16x16x32_bf16 v[64:67], v[226:229], v[210:213], 0
	v_mfma_f32_16x16x32_bf16 v[116:119], v[222:225], v[190:193], v[116:119]
	v_mfma_f32_16x16x32_bf16 v[108:111], v[230:233], v[190:193], v[108:111]
	v_mfma_f32_16x16x32_bf16 v[96:99], v[222:225], v[198:201], v[96:99]
	v_mfma_f32_16x16x32_bf16 v[88:91], v[230:233], v[198:201], v[88:91]
	v_mfma_f32_16x16x32_bf16 v[80:83], v[222:225], v[206:209], v[80:83]
	v_mfma_f32_16x16x32_bf16 v[72:75], v[230:233], v[206:209], v[72:75]
	v_mfma_f32_16x16x32_bf16 v[68:71], v[222:225], v[214:217], v[68:71]
	v_mfma_f32_16x16x32_bf16 v[64:67], v[230:233], v[214:217], v[64:67]
	s_setprio 0
	s_mov_b32 m0, s55
	v_lshl_add_u64 v[236:237], s[74:75], 0, v[128:129]
	s_barrier
	ds_read_b128 v[186:189], v161 offset:16384
	ds_read_b128 v[190:193], v161 offset:17408
	ds_read_b128 v[194:197], v161 offset:18432
	ds_read_b128 v[198:201], v161 offset:19456
	ds_read_b128 v[202:205], v161 offset:20480
	ds_read_b128 v[206:209], v161 offset:21504
	ds_read_b128 v[210:213], v161 offset:22528
	ds_read_b128 v[214:217], v161 offset:23552
	global_load_lds_dwordx4 v[236:237], off
	v_lshl_add_u64 v[238:239], s[74:75], 0, v[132:133]
	s_mov_b32 m0, s86
	s_nop 0
	global_load_lds_dwordx4 v[238:239], off
	s_barrier
	s_waitcnt lgkmcnt(0)
	s_setprio 1
	s_waitcnt lgkmcnt(0)
	v_mfma_f32_16x16x32_bf16 v[60:63], v[164:167], v[186:189], 0
	v_mfma_f32_16x16x32_bf16 v[56:59], v[178:181], v[186:189], 0
	v_mfma_f32_16x16x32_bf16 v[52:55], v[164:167], v[194:197], 0
	v_mfma_f32_16x16x32_bf16 v[44:47], v[178:181], v[194:197], 0
	v_mfma_f32_16x16x32_bf16 v[36:39], v[164:167], v[202:205], 0
	v_mfma_f32_16x16x32_bf16 v[28:31], v[178:181], v[202:205], 0
	v_mfma_f32_16x16x32_bf16 v[20:23], v[164:167], v[210:213], 0
	v_mfma_f32_16x16x32_bf16 v[12:15], v[178:181], v[210:213], 0
	v_mfma_f32_16x16x32_bf16 v[60:63], v[174:177], v[190:193], v[60:63]
	v_mfma_f32_16x16x32_bf16 v[56:59], v[182:185], v[190:193], v[56:59]
	v_mfma_f32_16x16x32_bf16 v[52:55], v[174:177], v[198:201], v[52:55]
	v_mfma_f32_16x16x32_bf16 v[44:47], v[182:185], v[198:201], v[44:47]
	v_mfma_f32_16x16x32_bf16 v[36:39], v[174:177], v[206:209], v[36:39]
	v_mfma_f32_16x16x32_bf16 v[28:31], v[182:185], v[206:209], v[28:31]
	v_mfma_f32_16x16x32_bf16 v[20:23], v[174:177], v[214:217], v[20:23]
	v_mfma_f32_16x16x32_bf16 v[12:15], v[182:185], v[214:217], v[12:15]
	s_setprio 0
	s_barrier
; #define PG8_STAGE(bufoff, gbase, voff) do { _Pragma("unroll") for (int _i = 0; _i < 2; ++_i) \
;         __builtin_amdgcn_global_load_lds((const unsigned*)((const char*)(gbase) + (voff)[_i]), (LAS unsigned*)(lds + (bufoff) + ldsw + _i * 8192), 16, 0, 0); } while (0)
; #define PG8_LDA(dst, b, h) do { _Pragma("unroll") for (int m = 0; m < 4; ++m) _Pragma("unroll") for (int k = 0; k < 2; ++k) dst[m][k] = *(const LAS bf16x8*)(lds + PG8_SA(b, h) + aoff + m * 2048 + k * 1024); } while (0)
; #define PG8_LDB(dst, b, h) do { _Pragma("unroll") for (int n = 0; n < 2; ++n) _Pragma("unroll") for (int k = 0; k < 2; ++k) dst[n][k] = *(const LAS bf16x8*)(lds + PG8_SB(b, h) + boff + n * 2048 + k * 1024); } while (0)
; #define PG8_MMA(ai, bj, At, Bt) do { __builtin_amdgcn_s_setprio(1); _Pragma("unroll") for (int m = 0; m < 4; ++m) _Pragma("unroll") for (int n = 0; n < 2; ++n) _Pragma("unroll") for (int k = 0; k < 2; ++k) \
;         acc[ai][bj][m][n] = __builtin_amdgcn_mfma_f32_16x16x32_bf16(Bt[n][k], At[m][k], acc[ai][bj][m][n], 0, 0, 0); __builtin_amdgcn_s_setprio(0); } while (0)
; #define PG8_WAIT_V(n) asm volatile("s_waitcnt vmcnt(" #n ")" ::: "memory")
; #define PG8_WAIT_L(n) asm volatile("s_waitcnt lgkmcnt(" #n ")" ::: "memory")
; #define PG8_BAR __builtin_amdgcn_s_barrier()
; #define PG8_SCHED __builtin_amdgcn_sched_barrier(0)
; template <class Epi, class Sched>
; __device__ __forceinline__ void gemm_phase(LAS unsigned char* lds, const int K, const Sched& S, const Epi& E) {
;     ...
;             PG8_STAGE(PG8_SB(0, 1), b2 + hstep, voffB);
;             PG8_WAIT_V(6); PG8_BAR; PG8_MMA(1, 1, At, B1); PG8_BAR;
;             PG8_LDB(B0, 1, 0); PG8_SCHED; PG8_LDA(At, 1, 0); PG8_STAGE(PG8_SA(0, 1), a2 + hstepA, voffA);
;             PG8_WAIT_L(8); PG8_BAR; PG8_WAIT_L(0); PG8_MMA(0, 0, At, B0); PG8_BAR; PG8_SCHED;
;             PG8_LDB(B1, 1, 1); PG8_STAGE(PG8_SB(1, 0), b3, voffB);
;             PG8_BAR; PG8_WAIT_L(0); PG8_MMA(0, 1, At, B1); PG8_BAR;
	s_add_u32 vcc_lo, s72, 0x40000
	s_addc_u32 vcc_hi, s73, 0
	s_add_i32 s79, s52, s54
	v_lshl_add_u64 v[164:165], vcc, 0, v[130:131]
	s_mov_b32 m0, s79
	s_nop 0
	global_load_lds_dwordx4 v[164:165], off
	v_lshl_add_u64 v[164:165], vcc, 0, v[134:135]
	s_add_i32 m0, s79, 0x2000
	s_nop 0
	global_load_lds_dwordx4 v[164:165], off
	s_waitcnt vmcnt(6)
	s_barrier
	s_setprio 1
	v_mfma_f32_16x16x32_bf16 v[48:51], v[218:221], v[186:189], 0
	v_mfma_f32_16x16x32_bf16 v[40:43], v[226:229], v[186:189], 0
	v_mfma_f32_16x16x32_bf16 v[32:35], v[218:221], v[194:197], 0
	v_mfma_f32_16x16x32_bf16 v[24:27], v[226:229], v[194:197], 0
	v_mfma_f32_16x16x32_bf16 v[16:19], v[218:221], v[202:205], 0
	v_mfma_f32_16x16x32_bf16 v[8:11], v[226:229], v[202:205], 0
	v_mfma_f32_16x16x32_bf16 v[4:7], v[218:221], v[210:213], 0
	v_mfma_f32_16x16x32_bf16 v[0:3], v[226:229], v[210:213], 0
	v_mfma_f32_16x16x32_bf16 v[48:51], v[222:225], v[190:193], v[48:51]
	v_mfma_f32_16x16x32_bf16 v[40:43], v[230:233], v[190:193], v[40:43]
	v_mfma_f32_16x16x32_bf16 v[32:35], v[222:225], v[198:201], v[32:35]
	v_mfma_f32_16x16x32_bf16 v[24:27], v[230:233], v[198:201], v[24:27]
	v_mfma_f32_16x16x32_bf16 v[16:19], v[222:225], v[206:209], v[16:19]
	v_mfma_f32_16x16x32_bf16 v[8:11], v[230:233], v[206:209], v[8:11]
	v_mfma_f32_16x16x32_bf16 v[4:7], v[222:225], v[214:217], v[4:7]
	v_mfma_f32_16x16x32_bf16 v[0:3], v[230:233], v[214:217], v[0:3]
	s_setprio 0
	s_add_i32 s79, 0, 0x18000
	v_add_u32_e32 v173, s79, v139
	s_barrier
	ds_read_b128 v[164:167], v173
	ds_read_b128 v[174:177], v173 offset:1024
	ds_read_b128 v[178:181], v173 offset:2048
	ds_read_b128 v[182:185], v173 offset:3072
	s_add_u32 s74, s74, 0x40000
	s_addc_u32 s75, s75, 0
	s_mov_b32 m0, s56
	v_lshl_add_u64 v[218:219], s[74:75], 0, v[128:129]
	ds_read_b128 v[186:189], v161 offset:32768
	ds_read_b128 v[190:193], v161 offset:33792
	ds_read_b128 v[194:197], v161 offset:34816
	ds_read_b128 v[198:201], v161 offset:35840
	ds_read_b128 v[202:205], v161 offset:36864
	ds_read_b128 v[206:209], v161 offset:37888
	ds_read_b128 v[210:213], v161 offset:38912
	ds_read_b128 v[214:217], v161 offset:39936
	global_load_lds_dwordx4 v[218:219], off
	v_lshl_add_u64 v[218:219], s[74:75], 0, v[132:133]
	s_mov_b32 m0, s57
	s_nop 0
	global_load_lds_dwordx4 v[218:219], off
	s_waitcnt lgkmcnt(8)
	s_barrier
	s_waitcnt lgkmcnt(0)
	s_setprio 1
	s_waitcnt lgkmcnt(0)
	v_mfma_f32_16x16x32_bf16 v[124:127], v[164:167], v[186:189], v[124:127]
	v_mfma_f32_16x16x32_bf16 v[120:123], v[178:181], v[186:189], v[120:123]
	v_mfma_f32_16x16x32_bf16 v[112:115], v[164:167], v[194:197], v[112:115]
	v_mfma_f32_16x16x32_bf16 v[104:107], v[178:181], v[194:197], v[104:107]
	v_mfma_f32_16x16x32_bf16 v[100:103], v[164:167], v[202:205], v[100:103]
	v_mfma_f32_16x16x32_bf16 v[92:95], v[178:181], v[202:205], v[92:95]
	v_mfma_f32_16x16x32_bf16 v[84:87], v[164:167], v[210:213], v[84:87]
	v_mfma_f32_16x16x32_bf16 v[76:79], v[178:181], v[210:213], v[76:79]
	v_mfma_f32_16x16x32_bf16 v[124:127], v[174:177], v[190:193], v[124:127]
	v_mfma_f32_16x16x32_bf16 v[120:123], v[182:185], v[190:193], v[120:123]
	v_mfma_f32_16x16x32_bf16 v[112:115], v[174:177], v[198:201], v[112:115]
	v_mfma_f32_16x16x32_bf16 v[104:107], v[182:185], v[198:201], v[104:107]
	v_mfma_f32_16x16x32_bf16 v[100:103], v[174:177], v[206:209], v[100:103]
	v_mfma_f32_16x16x32_bf16 v[92:95], v[182:185], v[206:209], v[92:95]
	v_mfma_f32_16x16x32_bf16 v[84:87], v[174:177], v[214:217], v[84:87]
	v_mfma_f32_16x16x32_bf16 v[76:79], v[182:185], v[214:217], v[76:79]
	s_setprio 0
	s_barrier
	s_add_i32 s74, 0, 0x1c000
	s_add_i32 s75, s79, s54
	v_add_u32_e32 v173, s74, v139
	v_lshl_add_u64 v[168:169], v[168:169], 0, s[38:39]
	s_mov_b32 m0, s75
	ds_read_b128 v[218:221], v173
	ds_read_b128 v[222:225], v173 offset:1024
	ds_read_b128 v[226:229], v173 offset:2048
	ds_read_b128 v[230:233], v173 offset:3072
	global_load_lds_dwordx4 v[168:169], off
	v_lshl_add_u64 v[168:169], v[234:235], 0, s[38:39]
	s_add_i32 m0, s75, 0x2000
	s_nop 0
	global_load_lds_dwordx4 v[168:169], off
	s_barrier
; #define PG8_STAGE(bufoff, gbase, voff) do { _Pragma("unroll") for (int _i = 0; _i < 2; ++_i) \
;         __builtin_amdgcn_global_load_lds((const unsigned*)((const char*)(gbase) + (voff)[_i]), (LAS unsigned*)(lds + (bufoff) + ldsw + _i * 8192), 16, 0, 0); } while (0)
; #define PG8_LDA(dst, b, h) do { _Pragma("unroll") for (int m = 0; m < 4; ++m) _Pragma("unroll") for (int k = 0; k < 2; ++k) dst[m][k] = *(const LAS bf16x8*)(lds + PG8_SA(b, h) + aoff + m * 2048 + k * 1024); } while (0)
; #define PG8_MMA(ai, bj, At, Bt) do { __builtin_amdgcn_s_setprio(1); _Pragma("unroll") for (int m = 0; m < 4; ++m) _Pragma("unroll") for (int n = 0; n < 2; ++n) _Pragma("unroll") for (int k = 0; k < 2; ++k) \
;         acc[ai][bj][m][n] = __builtin_amdgcn_mfma_f32_16x16x32_bf16(Bt[n][k], At[m][k], acc[ai][bj][m][n], 0, 0, 0); __builtin_amdgcn_s_setprio(0); } while (0)
; #define PG8_WAIT_V(n) asm volatile("s_waitcnt vmcnt(" #n ")" ::: "memory")
; #define PG8_WAIT_L(n) asm volatile("s_waitcnt lgkmcnt(" #n ")" ::: "memory")
; #define PG8_BAR __builtin_amdgcn_s_barrier()
; #define PG8_SCHED __builtin_amdgcn_sched_barrier(0)
; template <class Epi, class Sched>
; __device__ __forceinline__ void gemm_phase(LAS unsigned char* lds, const int K, const Sched& S, const Epi& E) {
;     ...
;             PG8_BAR; PG8_WAIT_L(0); PG8_MMA(0, 1, At, B1); PG8_BAR;
;             PG8_LDA(At, 1, 1); PG8_STAGE(PG8_SA(1, 0), a3, voffA);
;             PG8_BAR; PG8_WAIT_L(0); PG8_MMA(1, 0, At, B0); PG8_BAR; PG8_SCHED;
;             PG8_STAGE(PG8_SB(1, 1), b3 + hstep, voffB);
;             PG8_WAIT_V(6); PG8_BAR; PG8_MMA(1, 1, At, B1); PG8_BAR;
	s_waitcnt lgkmcnt(0)
	s_setprio 1
	s_waitcnt lgkmcnt(0)
	v_mfma_f32_16x16x32_bf16 v[116:119], v[218:221], v[186:189], v[116:119]
	v_mfma_f32_16x16x32_bf16 v[108:111], v[226:229], v[186:189], v[108:111]
	v_mfma_f32_16x16x32_bf16 v[96:99], v[218:221], v[194:197], v[96:99]
	v_mfma_f32_16x16x32_bf16 v[88:91], v[226:229], v[194:197], v[88:91]
	v_mfma_f32_16x16x32_bf16 v[80:83], v[218:221], v[202:205], v[80:83]
	v_mfma_f32_16x16x32_bf16 v[72:75], v[226:229], v[202:205], v[72:75]
	v_mfma_f32_16x16x32_bf16 v[68:71], v[218:221], v[210:213], v[68:71]
	v_mfma_f32_16x16x32_bf16 v[64:67], v[226:229], v[210:213], v[64:67]
	v_mfma_f32_16x16x32_bf16 v[116:119], v[222:225], v[190:193], v[116:119]
	v_mfma_f32_16x16x32_bf16 v[108:111], v[230:233], v[190:193], v[108:111]
	v_mfma_f32_16x16x32_bf16 v[96:99], v[222:225], v[198:201], v[96:99]
	v_mfma_f32_16x16x32_bf16 v[88:91], v[230:233], v[198:201], v[88:91]
	v_mfma_f32_16x16x32_bf16 v[80:83], v[222:225], v[206:209], v[80:83]
	v_mfma_f32_16x16x32_bf16 v[72:75], v[230:233], v[206:209], v[72:75]
	v_mfma_f32_16x16x32_bf16 v[68:71], v[222:225], v[214:217], v[68:71]
	v_mfma_f32_16x16x32_bf16 v[64:67], v[230:233], v[214:217], v[64:67]
	s_setprio 0
	s_mov_b32 m0, s58
	v_lshl_add_u64 v[168:169], v[236:237], 0, s[38:39]
	s_barrier
	ds_read_b128 v[186:189], v161 offset:49152
	ds_read_b128 v[190:193], v161 offset:50176
	ds_read_b128 v[194:197], v161 offset:51200
	ds_read_b128 v[198:201], v161 offset:52224
	ds_read_b128 v[202:205], v161 offset:53248
	ds_read_b128 v[206:209], v161 offset:54272
	ds_read_b128 v[210:213], v161 offset:55296
	ds_read_b128 v[214:217], v161 offset:56320
	global_load_lds_dwordx4 v[168:169], off
	v_lshl_add_u64 v[168:169], v[238:239], 0, s[38:39]
	s_mov_b32 m0, s59
	s_nop 0
	global_load_lds_dwordx4 v[168:169], off
	s_barrier
	s_waitcnt lgkmcnt(0)
	s_setprio 1
	s_waitcnt lgkmcnt(0)
	v_mfma_f32_16x16x32_bf16 v[60:63], v[164:167], v[186:189], v[60:63]
	v_mfma_f32_16x16x32_bf16 v[56:59], v[178:181], v[186:189], v[56:59]
	v_mfma_f32_16x16x32_bf16 v[52:55], v[164:167], v[194:197], v[52:55]
	v_mfma_f32_16x16x32_bf16 v[44:47], v[178:181], v[194:197], v[44:47]
	v_mfma_f32_16x16x32_bf16 v[36:39], v[164:167], v[202:205], v[36:39]
	v_mfma_f32_16x16x32_bf16 v[28:31], v[178:181], v[202:205], v[28:31]
	v_mfma_f32_16x16x32_bf16 v[20:23], v[164:167], v[210:213], v[20:23]
	v_mfma_f32_16x16x32_bf16 v[12:15], v[178:181], v[210:213], v[12:15]
	v_mfma_f32_16x16x32_bf16 v[60:63], v[174:177], v[190:193], v[60:63]
	v_mfma_f32_16x16x32_bf16 v[56:59], v[182:185], v[190:193], v[56:59]
	v_mfma_f32_16x16x32_bf16 v[52:55], v[174:177], v[198:201], v[52:55]
	v_mfma_f32_16x16x32_bf16 v[44:47], v[182:185], v[198:201], v[44:47]
	v_mfma_f32_16x16x32_bf16 v[36:39], v[174:177], v[206:209], v[36:39]
	v_mfma_f32_16x16x32_bf16 v[28:31], v[182:185], v[206:209], v[28:31]
	v_mfma_f32_16x16x32_bf16 v[20:23], v[174:177], v[214:217], v[20:23]
	v_mfma_f32_16x16x32_bf16 v[12:15], v[182:185], v[214:217], v[12:15]
	s_setprio 0
	s_barrier
	s_add_u32 s72, s72, 0x40080
	s_addc_u32 s73, s73, 0
	s_add_i32 s74, s74, s54
	v_lshl_add_u64 v[164:165], s[72:73], 0, v[130:131]
	s_mov_b32 m0, s74
	s_nop 0
	global_load_lds_dwordx4 v[164:165], off
	v_lshl_add_u64 v[164:165], s[72:73], 0, v[134:135]
	s_add_i32 m0, s74, 0x2000
	s_nop 0
	global_load_lds_dwordx4 v[164:165], off
	s_waitcnt vmcnt(6)
	s_barrier
	s_setprio 1
	v_mfma_f32_16x16x32_bf16 v[48:51], v[218:221], v[186:189], v[48:51]
	v_mfma_f32_16x16x32_bf16 v[40:43], v[226:229], v[186:189], v[40:43]
	v_mfma_f32_16x16x32_bf16 v[32:35], v[218:221], v[194:197], v[32:35]
	v_mfma_f32_16x16x32_bf16 v[24:27], v[226:229], v[194:197], v[24:27]
	v_mfma_f32_16x16x32_bf16 v[16:19], v[218:221], v[202:205], v[16:19]
	v_mfma_f32_16x16x32_bf16 v[8:11], v[226:229], v[202:205], v[8:11]
	v_mfma_f32_16x16x32_bf16 v[4:7], v[218:221], v[210:213], v[4:7]
	v_mfma_f32_16x16x32_bf16 v[0:3], v[226:229], v[210:213], v[0:3]
	v_mfma_f32_16x16x32_bf16 v[48:51], v[222:225], v[190:193], v[48:51]
	v_mfma_f32_16x16x32_bf16 v[40:43], v[230:233], v[190:193], v[40:43]
	v_mfma_f32_16x16x32_bf16 v[32:35], v[222:225], v[198:201], v[32:35]
	v_mfma_f32_16x16x32_bf16 v[24:27], v[230:233], v[198:201], v[24:27]
	v_mfma_f32_16x16x32_bf16 v[16:19], v[222:225], v[206:209], v[16:19]
	v_mfma_f32_16x16x32_bf16 v[8:11], v[230:233], v[206:209], v[8:11]
	v_mfma_f32_16x16x32_bf16 v[4:7], v[222:225], v[214:217], v[4:7]
	v_mfma_f32_16x16x32_bf16 v[0:3], v[230:233], v[214:217], v[0:3]
	s_setprio 0
	s_add_i32 s67, s67, 2
	s_add_u32 s70, s70, 0x100
	s_addc_u32 s71, s71, 0
	s_add_u32 s43, s43, 0x100
	s_addc_u32 s65, s65, 0
	s_cmp_gt_u32 s67, 13
	s_barrier

; #define PG8_STAGE(bufoff, gbase, voff) do { _Pragma("unroll") for (int _i = 0; _i < 2; ++_i) \
;         __builtin_amdgcn_global_load_lds((const unsigned*)((const char*)(gbase) + (voff)[_i]), (LAS unsigned*)(lds + (bufoff) + ldsw + _i * 8192), 16, 0, 0); } while (0)
; #define PG8_LDA(dst, b, h) do { _Pragma("unroll") for (int m = 0; m < 4; ++m) _Pragma("unroll") for (int k = 0; k < 2; ++k) dst[m][k] = *(const LAS bf16x8*)(lds + PG8_SA(b, h) + aoff + m * 2048 + k * 1024); } while (0)
; #define PG8_LDB(dst, b, h) do { _Pragma("unroll") for (int n = 0; n < 2; ++n) _Pragma("unroll") for (int k = 0; k < 2; ++k) dst[n][k] = *(const LAS bf16x8*)(lds + PG8_SB(b, h) + boff + n * 2048 + k * 1024); } while (0)
; #define PG8_MMA(ai, bj, At, Bt) do { __builtin_amdgcn_s_setprio(1); _Pragma("unroll") for (int m = 0; m < 4; ++m) _Pragma("unroll") for (int n = 0; n < 2; ++n) _Pragma("unroll") for (int k = 0; k < 2; ++k) \
;         acc[ai][bj][m][n] = __builtin_amdgcn_mfma_f32_16x16x32_bf16(Bt[n][k], At[m][k], acc[ai][bj][m][n], 0, 0, 0); __builtin_amdgcn_s_setprio(0); } while (0)
; #define PG8_WAIT_L(n) asm volatile("s_waitcnt lgkmcnt(" #n ")" ::: "memory")
; #define PG8_BAR __builtin_amdgcn_s_barrier()
; #define PG8_SCHED __builtin_amdgcn_sched_barrier(0)
; template <class Epi, class Sched>
; __device__ __forceinline__ void gemm_phase(LAS unsigned char* lds, const int K, const Sched& S, const Epi& E) {
;     ...
;             PG8_LDB(B0, 0, 0); PG8_SCHED; PG8_LDA(At, 0, 0); PG8_STAGE(PG8_SA(1, 1), a1 + hstepA, voffA);
;             PG8_WAIT_L(8); PG8_BAR; PG8_WAIT_L(0); PG8_MMA(0, 0, At, B0); PG8_BAR; PG8_SCHED;
;             PG8_LDB(B1, 0, 1); PG8_STAGE(PG8_SB(0, 0), b2, voffB);
;             PG8_BAR; PG8_WAIT_L(0); PG8_MMA(0, 1, At, B1); PG8_BAR;
;             PG8_LDA(At, 0, 1); PG8_STAGE(PG8_SA(0, 0), a2, voffA);
;             PG8_BAR; PG8_WAIT_L(0); PG8_MMA(1, 0, At, B0); PG8_BAR; PG8_SCHED;
;     ...
;                     for (int n = 0; n < 2; ++n) acc[a][b][m][n] = (f32x4){0.f, 0.f, 0.f, 0.f};
.LBB0_298:
	s_add_u32 s64, s64, 0x40080
	s_addc_u32 s65, s65, 0
	s_add_u32 s41, s66, 0x100
	s_addc_u32 s82, s67, 0
	s_mov_b32 s83, -2
.Lpeel_p3:
	ds_read_b128 v[156:159], v153
	ds_read_b128 v[160:163], v153 offset:1024
	ds_read_b128 v[164:167], v153 offset:2048
	ds_read_b128 v[174:177], v153 offset:3072
	s_add_u32 s66, s64, 0xfffc0080
	s_addc_u32 s67, s65, -1
	s_cmp_eq_u32 s83, 12
	s_cselect_b32 s69, s45, s67
	s_cselect_b32 s68, s44, s66
	s_cselect_b32 s67, s47, s82
	s_cselect_b32 s66, s46, s41
	v_lshl_add_u64 v[150:151], s[64:65], 0, v[144:145]
	s_add_i32 m0, s54, 0xc000
	ds_read_b128 v[178:181], v154
	ds_read_b128 v[182:185], v154 offset:1024
	ds_read_b128 v[186:189], v154 offset:2048
	ds_read_b128 v[190:193], v154 offset:3072
	ds_read_b128 v[194:197], v154 offset:4096
	ds_read_b128 v[198:201], v154 offset:5120
	ds_read_b128 v[202:205], v154 offset:6144
	ds_read_b128 v[206:209], v154 offset:7168
	global_load_lds_dwordx4 v[150:151], off
	v_lshl_add_u64 v[150:151], s[64:65], 0, v[146:147]
	s_add_i32 m0, s54, 0xe000
	s_nop 0
	global_load_lds_dwordx4 v[150:151], off
	s_waitcnt lgkmcnt(8)
	s_barrier
	s_waitcnt lgkmcnt(0)
	s_setprio 1
	s_waitcnt lgkmcnt(0)
	v_mfma_f32_16x16x32_bf16 v[124:127], v[156:159], v[178:181], 0
	v_mfma_f32_16x16x32_bf16 v[120:123], v[164:167], v[178:181], 0
	v_mfma_f32_16x16x32_bf16 v[116:119], v[156:159], v[186:189], 0
	v_mfma_f32_16x16x32_bf16 v[108:111], v[164:167], v[186:189], 0
	v_mfma_f32_16x16x32_bf16 v[100:103], v[156:159], v[194:197], 0
	v_mfma_f32_16x16x32_bf16 v[92:95], v[164:167], v[194:197], 0
	v_mfma_f32_16x16x32_bf16 v[84:87], v[156:159], v[202:205], 0
	v_mfma_f32_16x16x32_bf16 v[76:79], v[164:167], v[202:205], 0
	v_mfma_f32_16x16x32_bf16 v[124:127], v[160:163], v[182:185], v[124:127]
	v_mfma_f32_16x16x32_bf16 v[120:123], v[174:177], v[182:185], v[120:123]
	v_mfma_f32_16x16x32_bf16 v[116:119], v[160:163], v[190:193], v[116:119]
	v_mfma_f32_16x16x32_bf16 v[108:111], v[174:177], v[190:193], v[108:111]
	v_mfma_f32_16x16x32_bf16 v[100:103], v[160:163], v[198:201], v[100:103]
	v_mfma_f32_16x16x32_bf16 v[92:95], v[174:177], v[198:201], v[92:95]
	v_mfma_f32_16x16x32_bf16 v[84:87], v[160:163], v[206:209], v[84:87]
	v_mfma_f32_16x16x32_bf16 v[76:79], v[174:177], v[206:209], v[76:79]
	s_setprio 0
	s_barrier
	s_add_i32 s84, s72, s53
	v_lshl_add_u64 v[150:151], s[66:67], 0, v[136:137]
	s_mov_b32 m0, s84
	ds_read_b128 v[210:213], v155
	ds_read_b128 v[214:217], v155 offset:1024
	ds_read_b128 v[218:221], v155 offset:2048
	ds_read_b128 v[222:225], v155 offset:3072
	global_load_lds_dwordx4 v[150:151], off
	v_lshl_add_u64 v[168:169], s[66:67], 0, v[140:141]
	s_add_i32 m0, s84, 0x2000
	s_nop 0
	global_load_lds_dwordx4 v[168:169], off
	s_barrier
	s_waitcnt lgkmcnt(0)
	s_setprio 1
	s_waitcnt lgkmcnt(0)
	v_mfma_f32_16x16x32_bf16 v[112:115], v[210:213], v[178:181], 0
	v_mfma_f32_16x16x32_bf16 v[104:107], v[218:221], v[178:181], 0
	v_mfma_f32_16x16x32_bf16 v[96:99], v[210:213], v[186:189], 0
	v_mfma_f32_16x16x32_bf16 v[88:91], v[218:221], v[186:189], 0
	v_mfma_f32_16x16x32_bf16 v[80:83], v[210:213], v[194:197], 0
	v_mfma_f32_16x16x32_bf16 v[72:75], v[218:221], v[194:197], 0
	v_mfma_f32_16x16x32_bf16 v[68:71], v[210:213], v[202:205], 0
	v_mfma_f32_16x16x32_bf16 v[64:67], v[218:221], v[202:205], 0
	v_mfma_f32_16x16x32_bf16 v[112:115], v[214:217], v[182:185], v[112:115]
	v_mfma_f32_16x16x32_bf16 v[104:107], v[222:225], v[182:185], v[104:107]
	v_mfma_f32_16x16x32_bf16 v[96:99], v[214:217], v[190:193], v[96:99]
	v_mfma_f32_16x16x32_bf16 v[88:91], v[222:225], v[190:193], v[88:91]
	v_mfma_f32_16x16x32_bf16 v[80:83], v[214:217], v[198:201], v[80:83]
	v_mfma_f32_16x16x32_bf16 v[72:75], v[222:225], v[198:201], v[72:75]
	v_mfma_f32_16x16x32_bf16 v[68:71], v[214:217], v[206:209], v[68:71]
	v_mfma_f32_16x16x32_bf16 v[64:67], v[222:225], v[206:209], v[64:67]
	s_setprio 0
	s_mov_b32 m0, s54
	v_lshl_add_u64 v[226:227], s[68:69], 0, v[134:135]
	s_barrier
	ds_read_b128 v[178:181], v154 offset:16384
	ds_read_b128 v[182:185], v154 offset:17408
	ds_read_b128 v[186:189], v154 offset:18432
	ds_read_b128 v[190:193], v154 offset:19456
	ds_read_b128 v[194:197], v154 offset:20480
	ds_read_b128 v[198:201], v154 offset:21504
	ds_read_b128 v[202:205], v154 offset:22528
	ds_read_b128 v[206:209], v154 offset:23552
	global_load_lds_dwordx4 v[226:227], off
	v_lshl_add_u64 v[228:229], s[68:69], 0, v[138:139]
	s_mov_b32 m0, s55
	s_nop 0
	global_load_lds_dwordx4 v[228:229], off
	s_barrier
	s_waitcnt lgkmcnt(0)
	s_setprio 1
	s_waitcnt lgkmcnt(0)
	v_mfma_f32_16x16x32_bf16 v[60:63], v[156:159], v[178:181], 0
	v_mfma_f32_16x16x32_bf16 v[56:59], v[164:167], v[178:181], 0
	v_mfma_f32_16x16x32_bf16 v[52:55], v[156:159], v[186:189], 0
	v_mfma_f32_16x16x32_bf16 v[44:47], v[164:167], v[186:189], 0
	v_mfma_f32_16x16x32_bf16 v[36:39], v[156:159], v[194:197], 0
	v_mfma_f32_16x16x32_bf16 v[28:31], v[164:167], v[194:197], 0
	v_mfma_f32_16x16x32_bf16 v[20:23], v[156:159], v[202:205], 0
	v_mfma_f32_16x16x32_bf16 v[12:15], v[164:167], v[202:205], 0
	v_mfma_f32_16x16x32_bf16 v[60:63], v[160:163], v[182:185], v[60:63]
	v_mfma_f32_16x16x32_bf16 v[56:59], v[174:177], v[182:185], v[56:59]
	v_mfma_f32_16x16x32_bf16 v[52:55], v[160:163], v[190:193], v[52:55]
	v_mfma_f32_16x16x32_bf16 v[44:47], v[174:177], v[190:193], v[44:47]
	v_mfma_f32_16x16x32_bf16 v[36:39], v[160:163], v[198:201], v[36:39]
	v_mfma_f32_16x16x32_bf16 v[28:31], v[174:177], v[198:201], v[28:31]
	v_mfma_f32_16x16x32_bf16 v[20:23], v[160:163], v[206:209], v[20:23]
	v_mfma_f32_16x16x32_bf16 v[12:15], v[174:177], v[206:209], v[12:15]
	s_setprio 0
	s_barrier
; #define PG8_STAGE(bufoff, gbase, voff) do { _Pragma("unroll") for (int _i = 0; _i < 2; ++_i) \
;         __builtin_amdgcn_global_load_lds((const unsigned*)((const char*)(gbase) + (voff)[_i]), (LAS unsigned*)(lds + (bufoff) + ldsw + _i * 8192), 16, 0, 0); } while (0)
; #define PG8_LDA(dst, b, h) do { _Pragma("unroll") for (int m = 0; m < 4; ++m) _Pragma("unroll") for (int k = 0; k < 2; ++k) dst[m][k] = *(const LAS bf16x8*)(lds + PG8_SA(b, h) + aoff + m * 2048 + k * 1024); } while (0)
; #define PG8_LDB(dst, b, h) do { _Pragma("unroll") for (int n = 0; n < 2; ++n) _Pragma("unroll") for (int k = 0; k < 2; ++k) dst[n][k] = *(const LAS bf16x8*)(lds + PG8_SB(b, h) + boff + n * 2048 + k * 1024); } while (0)
; #define PG8_MMA(ai, bj, At, Bt) do { __builtin_amdgcn_s_setprio(1); _Pragma("unroll") for (int m = 0; m < 4; ++m) _Pragma("unroll") for (int n = 0; n < 2; ++n) _Pragma("unroll") for (int k = 0; k < 2; ++k) \
;         acc[ai][bj][m][n] = __builtin_amdgcn_mfma_f32_16x16x32_bf16(Bt[n][k], At[m][k], acc[ai][bj][m][n], 0, 0, 0); __builtin_amdgcn_s_setprio(0); } while (0)
; #define PG8_WAIT_V(n) asm volatile("s_waitcnt vmcnt(" #n ")" ::: "memory")
; #define PG8_WAIT_L(n) asm volatile("s_waitcnt lgkmcnt(" #n ")" ::: "memory")
; #define PG8_BAR __builtin_amdgcn_s_barrier()
; #define PG8_SCHED __builtin_amdgcn_sched_barrier(0)
; template <class Epi, class Sched>
; __device__ __forceinline__ void gemm_phase(LAS unsigned char* lds, const int K, const Sched& S, const Epi& E) {
;     ...
;             PG8_STAGE(PG8_SB(0, 1), b2 + hstep, voffB);
;             PG8_WAIT_V(6); PG8_BAR; PG8_MMA(1, 1, At, B1); PG8_BAR;
;             PG8_LDB(B0, 1, 0); PG8_SCHED; PG8_LDA(At, 1, 0); PG8_STAGE(PG8_SA(0, 1), a2 + hstepA, voffA);
;             PG8_WAIT_L(8); PG8_BAR; PG8_WAIT_L(0); PG8_MMA(0, 0, At, B0); PG8_BAR; PG8_SCHED;
;             PG8_LDB(B1, 1, 1); PG8_STAGE(PG8_SB(1, 0), b3, voffB);
;             PG8_BAR; PG8_WAIT_L(0); PG8_MMA(0, 1, At, B1); PG8_BAR;
	s_add_u32 s84, s66, 0x40000
	s_addc_u32 s85, s67, 0
	s_add_i32 s86, s73, s53
	v_lshl_add_u64 v[156:157], s[84:85], 0, v[136:137]
	s_mov_b32 m0, s86
	s_nop 0
	global_load_lds_dwordx4 v[156:157], off
	v_lshl_add_u64 v[156:157], s[84:85], 0, v[140:141]
	s_add_i32 m0, s86, 0x2000
	s_nop 0
	global_load_lds_dwordx4 v[156:157], off
	s_waitcnt vmcnt(6)
	s_barrier
	s_setprio 1
	v_mfma_f32_16x16x32_bf16 v[48:51], v[210:213], v[178:181], 0
	v_mfma_f32_16x16x32_bf16 v[40:43], v[218:221], v[178:181], 0
	v_mfma_f32_16x16x32_bf16 v[32:35], v[210:213], v[186:189], 0
	v_mfma_f32_16x16x32_bf16 v[24:27], v[218:221], v[186:189], 0
	v_mfma_f32_16x16x32_bf16 v[16:19], v[210:213], v[194:197], 0
	v_mfma_f32_16x16x32_bf16 v[8:11], v[218:221], v[194:197], 0
	v_mfma_f32_16x16x32_bf16 v[4:7], v[210:213], v[202:205], 0
	v_mfma_f32_16x16x32_bf16 v[0:3], v[218:221], v[202:205], 0
	v_mfma_f32_16x16x32_bf16 v[48:51], v[214:217], v[182:185], v[48:51]
	v_mfma_f32_16x16x32_bf16 v[40:43], v[222:225], v[182:185], v[40:43]
	v_mfma_f32_16x16x32_bf16 v[32:35], v[214:217], v[190:193], v[32:35]
	v_mfma_f32_16x16x32_bf16 v[24:27], v[222:225], v[190:193], v[24:27]
	v_mfma_f32_16x16x32_bf16 v[16:19], v[214:217], v[198:201], v[16:19]
	v_mfma_f32_16x16x32_bf16 v[8:11], v[222:225], v[198:201], v[8:11]
	v_mfma_f32_16x16x32_bf16 v[4:7], v[214:217], v[206:209], v[4:7]
	v_mfma_f32_16x16x32_bf16 v[0:3], v[222:225], v[206:209], v[0:3]
	s_setprio 0
	s_add_i32 s84, 0, 0x18000
	v_add_u32_e32 v149, s84, v152
	s_barrier
	ds_read_b128 v[156:159], v149
	ds_read_b128 v[160:163], v149 offset:1024
	ds_read_b128 v[164:167], v149 offset:2048
	ds_read_b128 v[174:177], v149 offset:3072
	s_add_u32 s68, s68, 0x40000
	s_addc_u32 s69, s69, 0
	s_mov_b32 m0, s56
	v_lshl_add_u64 v[210:211], s[68:69], 0, v[134:135]
	ds_read_b128 v[178:181], v154 offset:32768
	ds_read_b128 v[182:185], v154 offset:33792
	ds_read_b128 v[186:189], v154 offset:34816
	ds_read_b128 v[190:193], v154 offset:35840
	ds_read_b128 v[194:197], v154 offset:36864
	ds_read_b128 v[198:201], v154 offset:37888
	ds_read_b128 v[202:205], v154 offset:38912
	ds_read_b128 v[206:209], v154 offset:39936
	global_load_lds_dwordx4 v[210:211], off
	v_lshl_add_u64 v[210:211], s[68:69], 0, v[138:139]
	s_mov_b32 m0, s57
	s_nop 0
	global_load_lds_dwordx4 v[210:211], off
	s_waitcnt lgkmcnt(8)
	s_barrier
	s_waitcnt lgkmcnt(0)
	s_setprio 1
	s_waitcnt lgkmcnt(0)
	v_mfma_f32_16x16x32_bf16 v[124:127], v[156:159], v[178:181], v[124:127]
	v_mfma_f32_16x16x32_bf16 v[120:123], v[164:167], v[178:181], v[120:123]
	v_mfma_f32_16x16x32_bf16 v[116:119], v[156:159], v[186:189], v[116:119]
	v_mfma_f32_16x16x32_bf16 v[108:111], v[164:167], v[186:189], v[108:111]
	v_mfma_f32_16x16x32_bf16 v[100:103], v[156:159], v[194:197], v[100:103]
	v_mfma_f32_16x16x32_bf16 v[92:95], v[164:167], v[194:197], v[92:95]
	v_mfma_f32_16x16x32_bf16 v[84:87], v[156:159], v[202:205], v[84:87]
	v_mfma_f32_16x16x32_bf16 v[76:79], v[164:167], v[202:205], v[76:79]
	v_mfma_f32_16x16x32_bf16 v[124:127], v[160:163], v[182:185], v[124:127]
	v_mfma_f32_16x16x32_bf16 v[120:123], v[174:177], v[182:185], v[120:123]
	v_mfma_f32_16x16x32_bf16 v[116:119], v[160:163], v[190:193], v[116:119]
	v_mfma_f32_16x16x32_bf16 v[108:111], v[174:177], v[190:193], v[108:111]
	v_mfma_f32_16x16x32_bf16 v[100:103], v[160:163], v[198:201], v[100:103]
	v_mfma_f32_16x16x32_bf16 v[92:95], v[174:177], v[198:201], v[92:95]
	v_mfma_f32_16x16x32_bf16 v[84:87], v[160:163], v[206:209], v[84:87]
	v_mfma_f32_16x16x32_bf16 v[76:79], v[174:177], v[206:209], v[76:79]
	s_setprio 0
	s_barrier
	s_add_i32 s68, 0, 0x1c000
	s_add_i32 s69, s84, s53
	v_add_u32_e32 v149, s68, v152
	v_lshl_add_u64 v[150:151], v[150:151], 0, s[6:7]
	s_mov_b32 m0, s69
	ds_read_b128 v[210:213], v149
	ds_read_b128 v[214:217], v149 offset:1024
	ds_read_b128 v[218:221], v149 offset:2048
	ds_read_b128 v[222:225], v149 offset:3072
	global_load_lds_dwordx4 v[150:151], off
	v_lshl_add_u64 v[150:151], v[168:169], 0, s[6:7]
	s_add_i32 m0, s69, 0x2000
	s_nop 0
	global_load_lds_dwordx4 v[150:151], off
	s_barrier
; #define PG8_STAGE(bufoff, gbase, voff) do { _Pragma("unroll") for (int _i = 0; _i < 2; ++_i) \
;         __builtin_amdgcn_global_load_lds((const unsigned*)((const char*)(gbase) + (voff)[_i]), (LAS unsigned*)(lds + (bufoff) + ldsw + _i * 8192), 16, 0, 0); } while (0)
; #define PG8_LDA(dst, b, h) do { _Pragma("unroll") for (int m = 0; m < 4; ++m) _Pragma("unroll") for (int k = 0; k < 2; ++k) dst[m][k] = *(const LAS bf16x8*)(lds + PG8_SA(b, h) + aoff + m * 2048 + k * 1024); } while (0)
; #define PG8_MMA(ai, bj, At, Bt) do { __builtin_amdgcn_s_setprio(1); _Pragma("unroll") for (int m = 0; m < 4; ++m) _Pragma("unroll") for (int n = 0; n < 2; ++n) _Pragma("unroll") for (int k = 0; k < 2; ++k) \
;         acc[ai][bj][m][n] = __builtin_amdgcn_mfma_f32_16x16x32_bf16(Bt[n][k], At[m][k], acc[ai][bj][m][n], 0, 0, 0); __builtin_amdgcn_s_setprio(0); } while (0)
; #define PG8_WAIT_V(n) asm volatile("s_waitcnt vmcnt(" #n ")" ::: "memory")
; #define PG8_WAIT_L(n) asm volatile("s_waitcnt lgkmcnt(" #n ")" ::: "memory")
; #define PG8_BAR __builtin_amdgcn_s_barrier()
; #define PG8_SCHED __builtin_amdgcn_sched_barrier(0)
; template <class Epi, class Sched>
; __device__ __forceinline__ void gemm_phase(LAS unsigned char* lds, const int K, const Sched& S, const Epi& E) {
;     ...
;             PG8_BAR; PG8_WAIT_L(0); PG8_MMA(0, 1, At, B1); PG8_BAR;
;             PG8_LDA(At, 1, 1); PG8_STAGE(PG8_SA(1, 0), a3, voffA);
;             PG8_BAR; PG8_WAIT_L(0); PG8_MMA(1, 0, At, B0); PG8_BAR; PG8_SCHED;
;             PG8_STAGE(PG8_SB(1, 1), b3 + hstep, voffB);
;             PG8_WAIT_V(6); PG8_BAR; PG8_MMA(1, 1, At, B1); PG8_BAR;
	s_waitcnt lgkmcnt(0)
	s_setprio 1
	s_waitcnt lgkmcnt(0)
	v_mfma_f32_16x16x32_bf16 v[112:115], v[210:213], v[178:181], v[112:115]
	v_mfma_f32_16x16x32_bf16 v[104:107], v[218:221], v[178:181], v[104:107]
	v_mfma_f32_16x16x32_bf16 v[96:99], v[210:213], v[186:189], v[96:99]
	v_mfma_f32_16x16x32_bf16 v[88:91], v[218:221], v[186:189], v[88:91]
	v_mfma_f32_16x16x32_bf16 v[80:83], v[210:213], v[194:197], v[80:83]
	v_mfma_f32_16x16x32_bf16 v[72:75], v[218:221], v[194:197], v[72:75]
	v_mfma_f32_16x16x32_bf16 v[68:71], v[210:213], v[202:205], v[68:71]
	v_mfma_f32_16x16x32_bf16 v[64:67], v[218:221], v[202:205], v[64:67]
	v_mfma_f32_16x16x32_bf16 v[112:115], v[214:217], v[182:185], v[112:115]
	v_mfma_f32_16x16x32_bf16 v[104:107], v[222:225], v[182:185], v[104:107]
	v_mfma_f32_16x16x32_bf16 v[96:99], v[214:217], v[190:193], v[96:99]
	v_mfma_f32_16x16x32_bf16 v[88:91], v[222:225], v[190:193], v[88:91]
	v_mfma_f32_16x16x32_bf16 v[80:83], v[214:217], v[198:201], v[80:83]
	v_mfma_f32_16x16x32_bf16 v[72:75], v[222:225], v[198:201], v[72:75]
	v_mfma_f32_16x16x32_bf16 v[68:71], v[214:217], v[206:209], v[68:71]
	v_mfma_f32_16x16x32_bf16 v[64:67], v[222:225], v[206:209], v[64:67]
	s_setprio 0
	s_mov_b32 m0, s70
	v_lshl_add_u64 v[150:151], v[226:227], 0, s[6:7]
	s_barrier
	ds_read_b128 v[178:181], v154 offset:49152
	ds_read_b128 v[182:185], v154 offset:50176
	ds_read_b128 v[186:189], v154 offset:51200
	ds_read_b128 v[190:193], v154 offset:52224
	ds_read_b128 v[194:197], v154 offset:53248
	ds_read_b128 v[198:201], v154 offset:54272
	ds_read_b128 v[202:205], v154 offset:55296
	ds_read_b128 v[206:209], v154 offset:56320
	global_load_lds_dwordx4 v[150:151], off
	v_lshl_add_u64 v[150:151], v[228:229], 0, s[6:7]
	s_mov_b32 m0, s71
	s_nop 0
	global_load_lds_dwordx4 v[150:151], off
	s_barrier
	s_waitcnt lgkmcnt(0)
	s_setprio 1
	s_waitcnt lgkmcnt(0)
	v_mfma_f32_16x16x32_bf16 v[60:63], v[156:159], v[178:181], v[60:63]
	v_mfma_f32_16x16x32_bf16 v[56:59], v[164:167], v[178:181], v[56:59]
	v_mfma_f32_16x16x32_bf16 v[52:55], v[156:159], v[186:189], v[52:55]
	v_mfma_f32_16x16x32_bf16 v[44:47], v[164:167], v[186:189], v[44:47]
	v_mfma_f32_16x16x32_bf16 v[36:39], v[156:159], v[194:197], v[36:39]
	v_mfma_f32_16x16x32_bf16 v[28:31], v[164:167], v[194:197], v[28:31]
	v_mfma_f32_16x16x32_bf16 v[20:23], v[156:159], v[202:205], v[20:23]
	v_mfma_f32_16x16x32_bf16 v[12:15], v[164:167], v[202:205], v[12:15]
	v_mfma_f32_16x16x32_bf16 v[60:63], v[160:163], v[182:185], v[60:63]
	v_mfma_f32_16x16x32_bf16 v[56:59], v[174:177], v[182:185], v[56:59]
	v_mfma_f32_16x16x32_bf16 v[52:55], v[160:163], v[190:193], v[52:55]
	v_mfma_f32_16x16x32_bf16 v[44:47], v[174:177], v[190:193], v[44:47]
	v_mfma_f32_16x16x32_bf16 v[36:39], v[160:163], v[198:201], v[36:39]
	v_mfma_f32_16x16x32_bf16 v[28:31], v[174:177], v[198:201], v[28:31]
	v_mfma_f32_16x16x32_bf16 v[20:23], v[160:163], v[206:209], v[20:23]
	v_mfma_f32_16x16x32_bf16 v[12:15], v[174:177], v[206:209], v[12:15]
	s_setprio 0
	s_barrier
	s_add_u32 s66, s66, 0x40080
	s_addc_u32 s67, s67, 0
	s_add_i32 s68, s68, s53
	v_lshl_add_u64 v[150:151], s[66:67], 0, v[136:137]
	s_mov_b32 m0, s68
	s_nop 0
	global_load_lds_dwordx4 v[150:151], off
	v_lshl_add_u64 v[150:151], s[66:67], 0, v[140:141]
	s_add_i32 m0, s68, 0x2000
	s_nop 0
	global_load_lds_dwordx4 v[150:151], off
	s_waitcnt vmcnt(6)
	s_barrier
	s_setprio 1
	v_mfma_f32_16x16x32_bf16 v[48:51], v[210:213], v[178:181], v[48:51]
	v_mfma_f32_16x16x32_bf16 v[40:43], v[218:221], v[178:181], v[40:43]
	v_mfma_f32_16x16x32_bf16 v[32:35], v[210:213], v[186:189], v[32:35]
	v_mfma_f32_16x16x32_bf16 v[24:27], v[218:221], v[186:189], v[24:27]
	v_mfma_f32_16x16x32_bf16 v[16:19], v[210:213], v[194:197], v[16:19]
	v_mfma_f32_16x16x32_bf16 v[8:11], v[218:221], v[194:197], v[8:11]
	v_mfma_f32_16x16x32_bf16 v[4:7], v[210:213], v[202:205], v[4:7]
	v_mfma_f32_16x16x32_bf16 v[0:3], v[218:221], v[202:205], v[0:3]
	v_mfma_f32_16x16x32_bf16 v[48:51], v[214:217], v[182:185], v[48:51]
	v_mfma_f32_16x16x32_bf16 v[40:43], v[222:225], v[182:185], v[40:43]
	v_mfma_f32_16x16x32_bf16 v[32:35], v[214:217], v[190:193], v[32:35]
	v_mfma_f32_16x16x32_bf16 v[24:27], v[222:225], v[190:193], v[24:27]
	v_mfma_f32_16x16x32_bf16 v[16:19], v[214:217], v[198:201], v[16:19]
	v_mfma_f32_16x16x32_bf16 v[8:11], v[222:225], v[198:201], v[8:11]
	v_mfma_f32_16x16x32_bf16 v[4:7], v[214:217], v[206:209], v[4:7]
	v_mfma_f32_16x16x32_bf16 v[0:3], v[222:225], v[206:209], v[0:3]
	s_setprio 0
	s_add_i32 s83, s83, 2
	s_add_u32 s64, s64, 0x100
	s_addc_u32 s65, s65, 0
	s_add_u32 s41, s41, 0x100
	s_addc_u32 s82, s82, 0
	s_cmp_gt_u32 s83, 13
	s_barrier

;     __device__ __forceinline__ void run(const f32x4 (&v)[2][2][4][2], const Unit& u, int wr, int wc, int fr, int fq, LAS unsigned char* lds, int wid, int lane) const {
;     ...
;         if (wid == 0) { unsigned sp = 0;
;             while ((unsigned)__builtin_amdgcn_readfirstlane(__hip_atomic_load(cnt + 64 * u.pm, __ATOMIC_RELAXED, __HIP_MEMORY_SCOPE_AGENT)) < 32u) { __builtin_amdgcn_s_sleep(2); if (++sp > (1u << 22)) break; }
;             __builtin_amdgcn_fence(__ATOMIC_ACQUIRE, "agent"); }
;         asm volatile("s_waitcnt vmcnt(0) lgkmcnt(0)" ::: "memory"); __builtin_amdgcn_s_barrier(); asm volatile("" ::: "memory");
;         if (lane < 32) { const float* slot = xbuf + (size_t)(u.pm * BM + row) * 4; float t = 0.f;
; #pragma unroll
;             for (int k = 0; k < 4; ++k) t += __hip_atomic_load(slot + k, __ATOMIC_RELAXED, __HIP_MEMORY_SCOPE_AGENT);
;             S[row] = 1.0f / sqrtf(t * (1.0f / DM) + EPS); }
.LBB0_612:
.LBB0_613:
	s_waitcnt vmcnt(0) lgkmcnt(0)
	s_barrier
	s_and_saveexec_b64 s[6:7], s[0:1]
	s_cbranch_execz .LBB0_615
	v_lshl_add_u64 v[0:1], v[0:1], 4, s[12:13]
	global_load_dword v3, v[0:1], off sc1
	global_load_dword v128, v[0:1], off offset:4 sc1
	global_load_dword v129, v[0:1], off offset:8 sc1
	s_nop 0
	global_load_dword v0, v[0:1], off offset:12 sc1
	v_mov_b32_e32 v1, 0x358637bd
	s_mov_b32 s0, 0xf800000
	s_waitcnt vmcnt(3)
	v_add_f32_e32 v3, 0, v3
	s_waitcnt vmcnt(2)
	v_add_f32_e32 v3, v3, v128
	s_waitcnt vmcnt(1)
	v_add_f32_e32 v3, v3, v129
	s_waitcnt vmcnt(0)
	v_add_f32_e32 v0, v3, v0
	v_fmac_f32_e32 v1, 0x3a800000, v0
	v_mul_f32_e32 v0, 0x4f800000, v1
	v_cmp_gt_f32_e32 vcc, s0, v1
	v_mov_b32_e32 v3, 0x260
	s_nop 0
	v_cndmask_b32_e32 v0, v1, v0, vcc
	v_sqrt_f32_e32 v1, v0
	s_nop 0
	v_add_u32_e32 v128, -1, v1
	v_add_u32_e32 v129, 1, v1
	v_fma_f32 v130, -v128, v1, v0
	v_fma_f32 v131, -v129, v1, v0
	v_cmp_ge_f32_e64 s[0:1], 0, v130
	s_nop 1
	v_cndmask_b32_e64 v1, v1, v128, s[0:1]
	v_cmp_lt_f32_e64 s[0:1], 0, v131
	s_nop 1
	v_cndmask_b32_e64 v1, v1, v129, s[0:1]
	v_mul_f32_e32 v128, 0x37800000, v1
	v_cndmask_b32_e32 v1, v1, v128, vcc
	v_cmp_class_f32_e32 vcc, v0, v3
	s_nop 1
	v_cndmask_b32_e32 v0, v1, v0, vcc
	v_div_scale_f32 v1, s[0:1], v0, v0, 1.0
	v_rcp_f32_e32 v3, v1
	v_div_scale_f32 v128, vcc, 1.0, v0, 1.0
	v_fma_f32 v129, -v1, v3, 1.0
	v_fmac_f32_e32 v3, v129, v3
	v_mul_f32_e32 v129, v128, v3
	v_fma_f32 v130, -v1, v129, v128
	v_fmac_f32_e32 v129, v130, v3
	v_fma_f32 v1, -v1, v129, v128
	v_div_fmas_f32 v1, v1, v3, v129
	v_div_fixup_f32 v0, v1, v0, 1.0
	v_lshl_add_u32 v1, v2, 2, 0
	ds_write_b32 v1, v0 offset:4096

; #define PG8_STAGE(bufoff, gbase, voff) do { _Pragma("unroll") for (int _i = 0; _i < 2; ++_i) \
;         __builtin_amdgcn_global_load_lds((const unsigned*)((const char*)(gbase) + (voff)[_i]), (LAS unsigned*)(lds + (bufoff) + ldsw + _i * 8192), 16, 0, 0); } while (0)
; #define PG8_WAIT_V(n) asm volatile("s_waitcnt vmcnt(" #n ")" ::: "memory")
; #define PG8_BAR __builtin_amdgcn_s_barrier()
; template <class Epi, class Sched>
; __device__ __forceinline__ void gemm_phase(LAS unsigned char* lds, const int K, const Sched& S, const Epi& E) {
;     ...
;                 for (int n = 0; n < 2; ++n) acc[a][b][m][n] = (f32x4){0.f, 0.f, 0.f, 0.f};
;     ...
;     const char* cA = cur.pa; const char* cB = cur.pb;
;     PG8_STAGE(PG8_SB(0, 0), cB, voffB); PG8_STAGE(PG8_SA(0, 0), cA, voffA); PG8_STAGE(PG8_SB(0, 1), cB + hstep, voffB); PG8_STAGE(PG8_SA(0, 1), cA + hstepA, voffA);
;     if (wr == 1) PG8_BAR;
;     PG8_WAIT_V(4); PG8_BAR;
;     PG8_STAGE(PG8_SB(1, 0), cB + kstep, voffB); PG8_STAGE(PG8_SA(1, 0), cA + kstep, voffA); PG8_STAGE(PG8_SB(1, 1), cB + hstep + kstep, voffB);
;     PG8_WAIT_V(6); PG8_BAR;
.LBB0_1110:
	v_and_b32_e32 v8, 48, v170
	v_lshlrev_b32_e32 v10, 2, v156
	s_mov_b64 s[12:13], 0x80
	s_and_b32 s45, s9, 3
	v_lshl_or_b32 v9, v156, 6, v8
	s_lshl_b32 s11, s44, 13
	v_and_b32_e32 v10, 32, v10
	s_add_i32 m0, s46, 0x18000
	v_lshl_add_u64 v[6:7], v[6:7], 0, s[12:13]
	s_lshl_b32 s50, s44, 6
	v_bitop3_b32 v9, v9, s11, v10 bitop3:0xde
	s_lshl_b32 s11, s45, 12
	s_waitcnt vmcnt(4)
	s_barrier
	global_load_lds_dwordx4 v[6:7], off
	v_lshl_add_u64 v[4:5], v[4:5], 0, s[12:13]
	s_add_i32 m0, s46, 0x1a000
	s_add_i32 s33, s46, 0x8000
	s_add_i32 s52, s46, 0xa000
	global_load_lds_dwordx4 v[4:5], off
	v_lshl_add_u64 v[2:3], v[2:3], 0, s[12:13]
	s_mov_b32 m0, s33
	s_add_u32 s18, s24, 0xb0080
	global_load_lds_dwordx4 v[2:3], off
	v_lshl_add_u64 v[0:1], v[0:1], 0, s[12:13]
	s_mov_b32 m0, s52
	s_addc_u32 s19, s25, 0
	global_load_lds_dwordx4 v[0:1], off
	s_add_i32 m0, s46, 0x1c000
	v_lshl_add_u64 v[0:1], s[18:19], 0, v[144:145]
	global_load_lds_dwordx4 v[0:1], off
	v_lshl_add_u64 v[0:1], s[18:19], 0, v[146:147]
	s_add_i32 m0, s46, 0x1e000
	v_lshlrev_b32_e32 v10, 2, v170
	global_load_lds_dwordx4 v[0:1], off
	s_mov_b64 s[16:17], 0xb0080
	s_waitcnt vmcnt(6)
	v_add3_u32 v0, v159, v157, v158
	v_mov_b32_e32 v1, v145
	s_add_i32 s53, 0, 0x10000
	s_add_i32 s54, 0, 0x14000
	s_add_i32 s61, 0, 0x18000
	s_add_i32 s62, 0, 0x1c000
	v_or_b32_e32 v8, v161, v8
	v_and_b32_e32 v10, 32, v10
	v_lshl_add_u64 v[128:129], v[0:1], 0, s[16:17]
	v_add3_u32 v0, v160, v157, v158
	s_add_i32 s57, s53, s10
	s_add_i32 s59, s54, s10
	s_add_i32 s63, s61, s10
	s_add_i32 s65, s62, s10
	v_lshrrev_b32_e32 v136, 2, v170
	s_sext_i32_i8 s8, s8
	v_or_b32_e32 v152, s50, v156
	v_bitop3_b32 v137, s11, v8, v10 bitop3:0xf6
	v_lshl_add_u64 v[130:131], v[0:1], 0, s[16:17]
	v_add_u32_e32 v138, 0, v9
	s_add_i32 s55, s46, 0xc000
	s_add_i32 s56, s46, 0xe000
	s_add_i32 s58, s57, 0x2000
	s_add_i32 s60, s59, 0x2000
	s_add_i32 s64, s63, 0x2000
	s_add_i32 s66, s65, 0x2000
	s_mov_b64 s[16:17], s[24:25]
	s_barrier

; #define PG8_STAGE(bufoff, gbase, voff) do { _Pragma("unroll") for (int _i = 0; _i < 2; ++_i) \
;         __builtin_amdgcn_global_load_lds((const unsigned*)((const char*)(gbase) + (voff)[_i]), (LAS unsigned*)(lds + (bufoff) + ldsw + _i * 8192), 16, 0, 0); } while (0)
; #define PG8_LDA(dst, b, h) do { _Pragma("unroll") for (int m = 0; m < 4; ++m) _Pragma("unroll") for (int k = 0; k < 2; ++k) dst[m][k] = *(const LAS bf16x8*)(lds + PG8_SA(b, h) + aoff + m * 2048 + k * 1024); } while (0)
; #define PG8_LDB(dst, b, h) do { _Pragma("unroll") for (int n = 0; n < 2; ++n) _Pragma("unroll") for (int k = 0; k < 2; ++k) dst[n][k] = *(const LAS bf16x8*)(lds + PG8_SB(b, h) + boff + n * 2048 + k * 1024); } while (0)
; #define PG8_MMA(ai, bj, At, Bt) do { __builtin_amdgcn_s_setprio(1); _Pragma("unroll") for (int m = 0; m < 4; ++m) _Pragma("unroll") for (int n = 0; n < 2; ++n) _Pragma("unroll") for (int k = 0; k < 2; ++k) \
;         acc[ai][bj][m][n] = __builtin_amdgcn_mfma_f32_16x16x32_bf16(Bt[n][k], At[m][k], acc[ai][bj][m][n], 0, 0, 0); __builtin_amdgcn_s_setprio(0); } while (0)
; #define PG8_WAIT_L(n) asm volatile("s_waitcnt lgkmcnt(" #n ")" ::: "memory")
; #define PG8_BAR __builtin_amdgcn_s_barrier()
; #define PG8_SCHED __builtin_amdgcn_sched_barrier(0)
; template <class Epi, class Sched>
; __device__ __forceinline__ void gemm_phase(LAS unsigned char* lds, const int K, const Sched& S, const Epi& E) {
;     ...
;             PG8_LDB(B0, 0, 0); PG8_SCHED; PG8_LDA(At, 0, 0); PG8_STAGE(PG8_SA(1, 1), a1 + hstepA, voffA);
;             PG8_WAIT_L(8); PG8_BAR; PG8_WAIT_L(0); PG8_MMA(0, 0, At, B0); PG8_BAR; PG8_SCHED;
;             PG8_LDB(B1, 0, 1); PG8_STAGE(PG8_SB(0, 0), b2, voffB);
;             PG8_BAR; PG8_WAIT_L(0); PG8_MMA(0, 1, At, B1); PG8_BAR;
;             PG8_LDA(At, 0, 1); PG8_STAGE(PG8_SA(0, 0), a2, voffA);
;             PG8_BAR; PG8_WAIT_L(0); PG8_MMA(1, 0, At, B0); PG8_BAR; PG8_SCHED;
.Lpeel_p9:
	v_add_u32_e32 v139, s53, v137
	s_add_u32 s26, s0, s24
	ds_read_b128 v[140:143], v139
	ds_read_b128 v[148:151], v139 offset:1024
	ds_read_b128 v[158:161], v139 offset:2048
	ds_read_b128 v[162:165], v139 offset:3072
	s_addc_u32 s27, s1, s25
	s_add_u32 s26, s26, 0x100
	s_addc_u32 s27, s27, 0
	s_add_u32 s71, s11, s24
	s_addc_u32 s72, s69, s25
	s_cmpk_eq_i32 s24, 0x1500
	s_cselect_b32 s37, s23, s27
	s_cselect_b32 s36, s22, s26
	s_cselect_b32 s27, s17, s72
	s_cselect_b32 s26, s16, s71
	s_mov_b32 m0, s55
	v_lshl_add_u64 v[154:155], v[132:133], 0, s[24:25]
	ds_read_b128 v[166:169], v138
	ds_read_b128 v[172:175], v138 offset:1024
	ds_read_b128 v[176:179], v138 offset:2048
	ds_read_b128 v[180:183], v138 offset:3072
	ds_read_b128 v[184:187], v138 offset:4096
	ds_read_b128 v[188:191], v138 offset:5120
	ds_read_b128 v[192:195], v138 offset:6144
	ds_read_b128 v[196:199], v138 offset:7168
	global_load_lds_dwordx4 v[154:155], off
	v_lshl_add_u64 v[154:155], v[134:135], 0, s[24:25]
	s_mov_b32 m0, s56
	s_nop 0
	global_load_lds_dwordx4 v[154:155], off
	s_waitcnt lgkmcnt(8)
	s_barrier
	s_waitcnt lgkmcnt(0)
	s_setprio 1
	s_waitcnt lgkmcnt(0)
	v_mfma_f32_16x16x32_bf16 v[120:123], v[140:143], v[166:169], 0
	v_mfma_f32_16x16x32_bf16 v[124:127], v[158:161], v[166:169], 0
	v_mfma_f32_16x16x32_bf16 v[108:111], v[140:143], v[176:179], 0
	v_mfma_f32_16x16x32_bf16 v[104:107], v[158:161], v[176:179], 0
	v_mfma_f32_16x16x32_bf16 v[92:95], v[140:143], v[184:187], 0
	v_mfma_f32_16x16x32_bf16 v[88:91], v[158:161], v[184:187], 0
	v_mfma_f32_16x16x32_bf16 v[76:79], v[140:143], v[192:195], 0
	v_mfma_f32_16x16x32_bf16 v[72:75], v[158:161], v[192:195], 0
	v_mfma_f32_16x16x32_bf16 v[120:123], v[148:151], v[172:175], v[120:123]
	v_mfma_f32_16x16x32_bf16 v[124:127], v[162:165], v[172:175], v[124:127]
	v_mfma_f32_16x16x32_bf16 v[108:111], v[148:151], v[180:183], v[108:111]
	v_mfma_f32_16x16x32_bf16 v[104:107], v[162:165], v[180:183], v[104:107]
	v_mfma_f32_16x16x32_bf16 v[92:95], v[148:151], v[188:191], v[92:95]
	v_mfma_f32_16x16x32_bf16 v[88:91], v[162:165], v[188:191], v[88:91]
	v_mfma_f32_16x16x32_bf16 v[76:79], v[148:151], v[196:199], v[76:79]
	v_mfma_f32_16x16x32_bf16 v[72:75], v[162:165], v[196:199], v[72:75]
	s_setprio 0
	s_barrier
	s_mov_b32 m0, s57
	v_add_u32_e32 v139, s54, v137
	v_lshl_add_u64 v[154:155], s[26:27], 0, v[144:145]
	ds_read_b128 v[200:203], v139
	ds_read_b128 v[204:207], v139 offset:1024
	ds_read_b128 v[208:211], v139 offset:2048
	ds_read_b128 v[212:215], v139 offset:3072
	global_load_lds_dwordx4 v[154:155], off
	v_lshl_add_u64 v[216:217], s[26:27], 0, v[146:147]
	s_mov_b32 m0, s58
	s_nop 0
	global_load_lds_dwordx4 v[216:217], off
	s_barrier
	s_waitcnt lgkmcnt(0)
	s_setprio 1
	s_waitcnt lgkmcnt(0)
	v_mfma_f32_16x16x32_bf16 v[116:119], v[200:203], v[166:169], 0
	v_mfma_f32_16x16x32_bf16 v[112:115], v[208:211], v[166:169], 0
	v_mfma_f32_16x16x32_bf16 v[100:103], v[200:203], v[176:179], 0
	v_mfma_f32_16x16x32_bf16 v[96:99], v[208:211], v[176:179], 0
	v_mfma_f32_16x16x32_bf16 v[84:87], v[200:203], v[184:187], 0
	v_mfma_f32_16x16x32_bf16 v[80:83], v[208:211], v[184:187], 0
	v_mfma_f32_16x16x32_bf16 v[68:71], v[200:203], v[192:195], 0
	v_mfma_f32_16x16x32_bf16 v[64:67], v[208:211], v[192:195], 0
	v_mfma_f32_16x16x32_bf16 v[116:119], v[204:207], v[172:175], v[116:119]
	v_mfma_f32_16x16x32_bf16 v[112:115], v[212:215], v[172:175], v[112:115]
	v_mfma_f32_16x16x32_bf16 v[100:103], v[204:207], v[180:183], v[100:103]
	v_mfma_f32_16x16x32_bf16 v[96:99], v[212:215], v[180:183], v[96:99]
	v_mfma_f32_16x16x32_bf16 v[84:87], v[204:207], v[188:191], v[84:87]
	v_mfma_f32_16x16x32_bf16 v[80:83], v[212:215], v[188:191], v[80:83]
	v_mfma_f32_16x16x32_bf16 v[68:71], v[204:207], v[196:199], v[68:71]
	v_mfma_f32_16x16x32_bf16 v[64:67], v[212:215], v[196:199], v[64:67]
	s_setprio 0
	s_mov_b32 m0, s46
	v_lshl_add_u64 v[218:219], s[36:37], 0, v[144:145]
	s_barrier
	ds_read_b128 v[166:169], v138 offset:16384
	ds_read_b128 v[172:175], v138 offset:17408
	ds_read_b128 v[176:179], v138 offset:18432
	ds_read_b128 v[180:183], v138 offset:19456
	ds_read_b128 v[184:187], v138 offset:20480
	ds_read_b128 v[188:191], v138 offset:21504
	ds_read_b128 v[192:195], v138 offset:22528
	ds_read_b128 v[196:199], v138 offset:23552
	global_load_lds_dwordx4 v[218:219], off
	v_lshl_add_u64 v[220:221], s[36:37], 0, v[146:147]
	s_mov_b32 m0, s47
	s_nop 0
	global_load_lds_dwordx4 v[220:221], off
	s_barrier
	s_waitcnt lgkmcnt(0)
	s_setprio 1
	s_waitcnt lgkmcnt(0)
	v_mfma_f32_16x16x32_bf16 v[60:63], v[140:143], v[166:169], 0
	v_mfma_f32_16x16x32_bf16 v[56:59], v[158:161], v[166:169], 0
	v_mfma_f32_16x16x32_bf16 v[44:47], v[140:143], v[176:179], 0
	v_mfma_f32_16x16x32_bf16 v[40:43], v[158:161], v[176:179], 0
	v_mfma_f32_16x16x32_bf16 v[28:31], v[140:143], v[184:187], 0
	v_mfma_f32_16x16x32_bf16 v[24:27], v[158:161], v[184:187], 0
	v_mfma_f32_16x16x32_bf16 v[12:15], v[140:143], v[192:195], 0
	v_mfma_f32_16x16x32_bf16 v[8:11], v[158:161], v[192:195], 0
	v_mfma_f32_16x16x32_bf16 v[60:63], v[148:151], v[172:175], v[60:63]
	v_mfma_f32_16x16x32_bf16 v[56:59], v[162:165], v[172:175], v[56:59]
	v_mfma_f32_16x16x32_bf16 v[44:47], v[148:151], v[180:183], v[44:47]
	v_mfma_f32_16x16x32_bf16 v[40:43], v[162:165], v[180:183], v[40:43]
	v_mfma_f32_16x16x32_bf16 v[28:31], v[148:151], v[188:191], v[28:31]
	v_mfma_f32_16x16x32_bf16 v[24:27], v[162:165], v[188:191], v[24:27]
	v_mfma_f32_16x16x32_bf16 v[12:15], v[148:151], v[196:199], v[12:15]
	v_mfma_f32_16x16x32_bf16 v[8:11], v[162:165], v[196:199], v[8:11]
	s_setprio 0
	s_barrier
; #define PG8_STAGE(bufoff, gbase, voff) do { _Pragma("unroll") for (int _i = 0; _i < 2; ++_i) \
;         __builtin_amdgcn_global_load_lds((const unsigned*)((const char*)(gbase) + (voff)[_i]), (LAS unsigned*)(lds + (bufoff) + ldsw + _i * 8192), 16, 0, 0); } while (0)
; #define PG8_LDA(dst, b, h) do { _Pragma("unroll") for (int m = 0; m < 4; ++m) _Pragma("unroll") for (int k = 0; k < 2; ++k) dst[m][k] = *(const LAS bf16x8*)(lds + PG8_SA(b, h) + aoff + m * 2048 + k * 1024); } while (0)
; #define PG8_LDB(dst, b, h) do { _Pragma("unroll") for (int n = 0; n < 2; ++n) _Pragma("unroll") for (int k = 0; k < 2; ++k) dst[n][k] = *(const LAS bf16x8*)(lds + PG8_SB(b, h) + boff + n * 2048 + k * 1024); } while (0)
; #define PG8_MMA(ai, bj, At, Bt) do { __builtin_amdgcn_s_setprio(1); _Pragma("unroll") for (int m = 0; m < 4; ++m) _Pragma("unroll") for (int n = 0; n < 2; ++n) _Pragma("unroll") for (int k = 0; k < 2; ++k) \
;         acc[ai][bj][m][n] = __builtin_amdgcn_mfma_f32_16x16x32_bf16(Bt[n][k], At[m][k], acc[ai][bj][m][n], 0, 0, 0); __builtin_amdgcn_s_setprio(0); } while (0)
; #define PG8_WAIT_V(n) asm volatile("s_waitcnt vmcnt(" #n ")" ::: "memory")
; #define PG8_WAIT_L(n) asm volatile("s_waitcnt lgkmcnt(" #n ")" ::: "memory")
; #define PG8_BAR __builtin_amdgcn_s_barrier()
; #define PG8_SCHED __builtin_amdgcn_sched_barrier(0)
; template <class Epi, class Sched>
; __device__ __forceinline__ void gemm_phase(LAS unsigned char* lds, const int K, const Sched& S, const Epi& E) {
;     ...
;             PG8_STAGE(PG8_SB(0, 1), b2 + hstep, voffB);
;             PG8_WAIT_V(6); PG8_BAR; PG8_MMA(1, 1, At, B1); PG8_BAR;
;             PG8_LDB(B0, 1, 0); PG8_SCHED; PG8_LDA(At, 1, 0); PG8_STAGE(PG8_SA(0, 1), a2 + hstepA, voffA);
;             PG8_WAIT_L(8); PG8_BAR; PG8_WAIT_L(0); PG8_MMA(0, 0, At, B0); PG8_BAR; PG8_SCHED;
;             PG8_LDB(B1, 1, 1); PG8_STAGE(PG8_SB(1, 0), b3, voffB);
;             PG8_BAR; PG8_WAIT_L(0); PG8_MMA(0, 1, At, B1); PG8_BAR;
	s_add_u32 s72, s26, 0xb0000
	s_addc_u32 s73, s27, 0
	s_mov_b32 m0, s59
	v_lshl_add_u64 v[140:141], s[72:73], 0, v[144:145]
	global_load_lds_dwordx4 v[140:141], off
	v_lshl_add_u64 v[140:141], s[72:73], 0, v[146:147]
	s_mov_b32 m0, s60
	s_nop 0
	global_load_lds_dwordx4 v[140:141], off
	s_waitcnt vmcnt(6)
	s_barrier
	s_setprio 1
	v_mfma_f32_16x16x32_bf16 v[52:55], v[200:203], v[166:169], 0
	v_mfma_f32_16x16x32_bf16 v[48:51], v[208:211], v[166:169], 0
	v_mfma_f32_16x16x32_bf16 v[36:39], v[200:203], v[176:179], 0
	v_mfma_f32_16x16x32_bf16 v[32:35], v[208:211], v[176:179], 0
	v_mfma_f32_16x16x32_bf16 v[20:23], v[200:203], v[184:187], 0
	v_mfma_f32_16x16x32_bf16 v[16:19], v[208:211], v[184:187], 0
	v_mfma_f32_16x16x32_bf16 v[4:7], v[200:203], v[192:195], 0
	v_mfma_f32_16x16x32_bf16 v[0:3], v[208:211], v[192:195], 0
	v_mfma_f32_16x16x32_bf16 v[52:55], v[204:207], v[172:175], v[52:55]
	v_mfma_f32_16x16x32_bf16 v[48:51], v[212:215], v[172:175], v[48:51]
	v_mfma_f32_16x16x32_bf16 v[36:39], v[204:207], v[180:183], v[36:39]
	v_mfma_f32_16x16x32_bf16 v[32:35], v[212:215], v[180:183], v[32:35]
	v_mfma_f32_16x16x32_bf16 v[20:23], v[204:207], v[188:191], v[20:23]
	v_mfma_f32_16x16x32_bf16 v[16:19], v[212:215], v[188:191], v[16:19]
	v_mfma_f32_16x16x32_bf16 v[4:7], v[204:207], v[196:199], v[4:7]
	v_mfma_f32_16x16x32_bf16 v[0:3], v[212:215], v[196:199], v[0:3]
	s_setprio 0
	v_add_u32_e32 v139, s61, v137
	s_barrier
	ds_read_b128 v[140:143], v139
	ds_read_b128 v[148:151], v139 offset:1024
	ds_read_b128 v[158:161], v139 offset:2048
	ds_read_b128 v[162:165], v139 offset:3072
	s_add_u32 s36, s36, 0xb0000
	s_addc_u32 s37, s37, 0
	s_mov_b32 m0, s48
	v_lshl_add_u64 v[200:201], s[36:37], 0, v[144:145]
	ds_read_b128 v[166:169], v138 offset:32768
	ds_read_b128 v[172:175], v138 offset:33792
	ds_read_b128 v[176:179], v138 offset:34816
	ds_read_b128 v[180:183], v138 offset:35840
	ds_read_b128 v[184:187], v138 offset:36864
	ds_read_b128 v[188:191], v138 offset:37888
	ds_read_b128 v[192:195], v138 offset:38912
	ds_read_b128 v[196:199], v138 offset:39936
	global_load_lds_dwordx4 v[200:201], off
	v_lshl_add_u64 v[200:201], s[36:37], 0, v[146:147]
	s_mov_b32 m0, s49
	s_nop 0
	global_load_lds_dwordx4 v[200:201], off
	s_waitcnt lgkmcnt(8)
	s_barrier
	s_waitcnt lgkmcnt(0)
	s_setprio 1
	s_waitcnt lgkmcnt(0)
	v_mfma_f32_16x16x32_bf16 v[120:123], v[140:143], v[166:169], v[120:123]
	v_mfma_f32_16x16x32_bf16 v[124:127], v[158:161], v[166:169], v[124:127]
	v_mfma_f32_16x16x32_bf16 v[108:111], v[140:143], v[176:179], v[108:111]
	v_mfma_f32_16x16x32_bf16 v[104:107], v[158:161], v[176:179], v[104:107]
	v_mfma_f32_16x16x32_bf16 v[92:95], v[140:143], v[184:187], v[92:95]
	v_mfma_f32_16x16x32_bf16 v[88:91], v[158:161], v[184:187], v[88:91]
	v_mfma_f32_16x16x32_bf16 v[76:79], v[140:143], v[192:195], v[76:79]
	v_mfma_f32_16x16x32_bf16 v[72:75], v[158:161], v[192:195], v[72:75]
	v_mfma_f32_16x16x32_bf16 v[120:123], v[148:151], v[172:175], v[120:123]
	v_mfma_f32_16x16x32_bf16 v[124:127], v[162:165], v[172:175], v[124:127]
	v_mfma_f32_16x16x32_bf16 v[108:111], v[148:151], v[180:183], v[108:111]
	v_mfma_f32_16x16x32_bf16 v[104:107], v[162:165], v[180:183], v[104:107]
	v_mfma_f32_16x16x32_bf16 v[92:95], v[148:151], v[188:191], v[92:95]
	v_mfma_f32_16x16x32_bf16 v[88:91], v[162:165], v[188:191], v[88:91]
	v_mfma_f32_16x16x32_bf16 v[76:79], v[148:151], v[196:199], v[76:79]
	v_mfma_f32_16x16x32_bf16 v[72:75], v[162:165], v[196:199], v[72:75]
	s_setprio 0
	s_barrier
	s_mov_b32 m0, s63
	v_add_u32_e32 v139, s62, v137
	v_lshl_add_u64 v[154:155], v[154:155], 0, s[12:13]
	ds_read_b128 v[200:203], v139
	ds_read_b128 v[204:207], v139 offset:1024
	ds_read_b128 v[208:211], v139 offset:2048
	ds_read_b128 v[212:215], v139 offset:3072
	global_load_lds_dwordx4 v[154:155], off
	v_lshl_add_u64 v[154:155], v[216:217], 0, s[12:13]
	s_mov_b32 m0, s64
	s_nop 0
	global_load_lds_dwordx4 v[154:155], off
	s_barrier
; #define PG8_STAGE(bufoff, gbase, voff) do { _Pragma("unroll") for (int _i = 0; _i < 2; ++_i) \
;         __builtin_amdgcn_global_load_lds((const unsigned*)((const char*)(gbase) + (voff)[_i]), (LAS unsigned*)(lds + (bufoff) + ldsw + _i * 8192), 16, 0, 0); } while (0)
; #define PG8_LDA(dst, b, h) do { _Pragma("unroll") for (int m = 0; m < 4; ++m) _Pragma("unroll") for (int k = 0; k < 2; ++k) dst[m][k] = *(const LAS bf16x8*)(lds + PG8_SA(b, h) + aoff + m * 2048 + k * 1024); } while (0)
; #define PG8_MMA(ai, bj, At, Bt) do { __builtin_amdgcn_s_setprio(1); _Pragma("unroll") for (int m = 0; m < 4; ++m) _Pragma("unroll") for (int n = 0; n < 2; ++n) _Pragma("unroll") for (int k = 0; k < 2; ++k) \
;         acc[ai][bj][m][n] = __builtin_amdgcn_mfma_f32_16x16x32_bf16(Bt[n][k], At[m][k], acc[ai][bj][m][n], 0, 0, 0); __builtin_amdgcn_s_setprio(0); } while (0)
; #define PG8_WAIT_V(n) asm volatile("s_waitcnt vmcnt(" #n ")" ::: "memory")
; #define PG8_WAIT_L(n) asm volatile("s_waitcnt lgkmcnt(" #n ")" ::: "memory")
; #define PG8_BAR __builtin_amdgcn_s_barrier()
; #define PG8_SCHED __builtin_amdgcn_sched_barrier(0)
; template <class Epi, class Sched>
; __device__ __forceinline__ void gemm_phase(LAS unsigned char* lds, const int K, const Sched& S, const Epi& E) {
;     ...
;             PG8_BAR; PG8_WAIT_L(0); PG8_MMA(0, 1, At, B1); PG8_BAR;
;             PG8_LDA(At, 1, 1); PG8_STAGE(PG8_SA(1, 0), a3, voffA);
;             PG8_BAR; PG8_WAIT_L(0); PG8_MMA(1, 0, At, B0); PG8_BAR; PG8_SCHED;
;             PG8_STAGE(PG8_SB(1, 1), b3 + hstep, voffB);
;             PG8_WAIT_V(6); PG8_BAR; PG8_MMA(1, 1, At, B1); PG8_BAR;
	s_waitcnt lgkmcnt(0)
	s_setprio 1
	s_waitcnt lgkmcnt(0)
	v_mfma_f32_16x16x32_bf16 v[116:119], v[200:203], v[166:169], v[116:119]
	v_mfma_f32_16x16x32_bf16 v[112:115], v[208:211], v[166:169], v[112:115]
	v_mfma_f32_16x16x32_bf16 v[100:103], v[200:203], v[176:179], v[100:103]
	v_mfma_f32_16x16x32_bf16 v[96:99], v[208:211], v[176:179], v[96:99]
	v_mfma_f32_16x16x32_bf16 v[84:87], v[200:203], v[184:187], v[84:87]
	v_mfma_f32_16x16x32_bf16 v[80:83], v[208:211], v[184:187], v[80:83]
	v_mfma_f32_16x16x32_bf16 v[68:71], v[200:203], v[192:195], v[68:71]
	v_mfma_f32_16x16x32_bf16 v[64:67], v[208:211], v[192:195], v[64:67]
	v_mfma_f32_16x16x32_bf16 v[116:119], v[204:207], v[172:175], v[116:119]
	v_mfma_f32_16x16x32_bf16 v[112:115], v[212:215], v[172:175], v[112:115]
	v_mfma_f32_16x16x32_bf16 v[100:103], v[204:207], v[180:183], v[100:103]
	v_mfma_f32_16x16x32_bf16 v[96:99], v[212:215], v[180:183], v[96:99]
	v_mfma_f32_16x16x32_bf16 v[84:87], v[204:207], v[188:191], v[84:87]
	v_mfma_f32_16x16x32_bf16 v[80:83], v[212:215], v[188:191], v[80:83]
	v_mfma_f32_16x16x32_bf16 v[68:71], v[204:207], v[196:199], v[68:71]
	v_mfma_f32_16x16x32_bf16 v[64:67], v[212:215], v[196:199], v[64:67]
	s_setprio 0
	s_mov_b32 m0, s33
	v_lshl_add_u64 v[154:155], v[218:219], 0, s[12:13]
	s_barrier
	ds_read_b128 v[166:169], v138 offset:49152
	ds_read_b128 v[172:175], v138 offset:50176
	ds_read_b128 v[176:179], v138 offset:51200
	ds_read_b128 v[180:183], v138 offset:52224
	ds_read_b128 v[184:187], v138 offset:53248
	ds_read_b128 v[188:191], v138 offset:54272
	ds_read_b128 v[192:195], v138 offset:55296
	ds_read_b128 v[196:199], v138 offset:56320
	global_load_lds_dwordx4 v[154:155], off
	v_lshl_add_u64 v[154:155], v[220:221], 0, s[12:13]
	s_mov_b32 m0, s52
	s_nop 0
	global_load_lds_dwordx4 v[154:155], off
	s_barrier
	s_waitcnt lgkmcnt(0)
	s_setprio 1
	s_waitcnt lgkmcnt(0)
	v_mfma_f32_16x16x32_bf16 v[60:63], v[140:143], v[166:169], v[60:63]
	v_mfma_f32_16x16x32_bf16 v[56:59], v[158:161], v[166:169], v[56:59]
	v_mfma_f32_16x16x32_bf16 v[44:47], v[140:143], v[176:179], v[44:47]
	v_mfma_f32_16x16x32_bf16 v[40:43], v[158:161], v[176:179], v[40:43]
	v_mfma_f32_16x16x32_bf16 v[28:31], v[140:143], v[184:187], v[28:31]
	v_mfma_f32_16x16x32_bf16 v[24:27], v[158:161], v[184:187], v[24:27]
	v_mfma_f32_16x16x32_bf16 v[12:15], v[140:143], v[192:195], v[12:15]
	v_mfma_f32_16x16x32_bf16 v[8:11], v[158:161], v[192:195], v[8:11]
	v_mfma_f32_16x16x32_bf16 v[60:63], v[148:151], v[172:175], v[60:63]
	v_mfma_f32_16x16x32_bf16 v[56:59], v[162:165], v[172:175], v[56:59]
	v_mfma_f32_16x16x32_bf16 v[44:47], v[148:151], v[180:183], v[44:47]
	v_mfma_f32_16x16x32_bf16 v[40:43], v[162:165], v[180:183], v[40:43]
	v_mfma_f32_16x16x32_bf16 v[28:31], v[148:151], v[188:191], v[28:31]
	v_mfma_f32_16x16x32_bf16 v[24:27], v[162:165], v[188:191], v[24:27]
	v_mfma_f32_16x16x32_bf16 v[12:15], v[148:151], v[196:199], v[12:15]
	v_mfma_f32_16x16x32_bf16 v[8:11], v[162:165], v[196:199], v[8:11]
	s_setprio 0
	s_barrier
	s_add_u32 s26, s26, 0xb0080
	s_addc_u32 s27, s27, 0
	s_mov_b32 m0, s65
	v_lshl_add_u64 v[140:141], s[26:27], 0, v[144:145]
	global_load_lds_dwordx4 v[140:141], off
	v_lshl_add_u64 v[140:141], s[26:27], 0, v[146:147]
	s_mov_b32 m0, s66
	s_nop 0
	global_load_lds_dwordx4 v[140:141], off
	s_waitcnt vmcnt(6)
	s_barrier
	s_setprio 1
	v_mfma_f32_16x16x32_bf16 v[52:55], v[200:203], v[166:169], v[52:55]
	v_mfma_f32_16x16x32_bf16 v[48:51], v[208:211], v[166:169], v[48:51]
	v_mfma_f32_16x16x32_bf16 v[36:39], v[200:203], v[176:179], v[36:39]
	v_mfma_f32_16x16x32_bf16 v[32:35], v[208:211], v[176:179], v[32:35]
	v_mfma_f32_16x16x32_bf16 v[20:23], v[200:203], v[184:187], v[20:23]
	v_mfma_f32_16x16x32_bf16 v[16:19], v[208:211], v[184:187], v[16:19]
	v_mfma_f32_16x16x32_bf16 v[4:7], v[200:203], v[192:195], v[4:7]
	v_mfma_f32_16x16x32_bf16 v[0:3], v[208:211], v[192:195], v[0:3]
	v_mfma_f32_16x16x32_bf16 v[52:55], v[204:207], v[172:175], v[52:55]
	v_mfma_f32_16x16x32_bf16 v[48:51], v[212:215], v[172:175], v[48:51]
	v_mfma_f32_16x16x32_bf16 v[36:39], v[204:207], v[180:183], v[36:39]
	v_mfma_f32_16x16x32_bf16 v[32:35], v[212:215], v[180:183], v[32:35]
	v_mfma_f32_16x16x32_bf16 v[20:23], v[204:207], v[188:191], v[20:23]
	v_mfma_f32_16x16x32_bf16 v[16:19], v[212:215], v[188:191], v[16:19]
	v_mfma_f32_16x16x32_bf16 v[4:7], v[204:207], v[196:199], v[4:7]
	v_mfma_f32_16x16x32_bf16 v[0:3], v[212:215], v[196:199], v[0:3]
	s_setprio 0
	s_add_i32 s70, s70, 2
	s_add_u32 s24, s24, 0x100
	s_addc_u32 s25, s25, 0
	s_cmp_gt_u32 s70, 41
	s_barrier

;     __device__ __forceinline__ void run(const f32x4 (&v)[2][2][4][2], const Unit& u, int wr, int wc, int fr, int fq, LAS unsigned char* lds, int wid, int lane) const {
;     ...
;         if (wid == 0) { unsigned sp = 0;
;             while ((unsigned)__builtin_amdgcn_readfirstlane(__hip_atomic_load(cnt + 64 * u.pm, __ATOMIC_RELAXED, __HIP_MEMORY_SCOPE_AGENT)) < 32u) { __builtin_amdgcn_s_sleep(2); if (++sp > (1u << 22)) break; }
;             __builtin_amdgcn_fence(__ATOMIC_ACQUIRE, "agent"); }
;         asm volatile("s_waitcnt vmcnt(0) lgkmcnt(0)" ::: "memory"); __builtin_amdgcn_s_barrier(); asm volatile("" ::: "memory");
;         if (lane < 32) { const float* slot = xbuf + (size_t)(u.pm * BM + row) * 4; float t = 0.f;
; #pragma unroll
;             for (int k = 0; k < 4; ++k) t += __hip_atomic_load(slot + k, __ATOMIC_RELAXED, __HIP_MEMORY_SCOPE_AGENT);
;             S[row] = 1.0f / sqrtf(t * (1.0f / DM) + EPS); }
.LBB0_1155:
.LBB0_1156:
	s_waitcnt vmcnt(0) lgkmcnt(0)
	s_barrier
	s_and_saveexec_b64 s[8:9], s[0:1]
	s_cbranch_execz .LBB0_1158
	v_lshl_add_u64 v[128:129], v[128:129], 4, s[6:7]
	global_load_dword v131, v[128:129], off sc1
	global_load_dword v132, v[128:129], off offset:4 sc1
	global_load_dword v133, v[128:129], off offset:8 sc1
	s_nop 0
	global_load_dword v128, v[128:129], off offset:12 sc1
	v_mov_b32_e32 v129, 0x358637bd
	s_mov_b32 s0, 0xf800000
	s_waitcnt vmcnt(3)
	v_add_f32_e32 v131, 0, v131
	s_waitcnt vmcnt(2)
	v_add_f32_e32 v131, v131, v132
	s_waitcnt vmcnt(1)
	v_add_f32_e32 v131, v131, v133
	s_waitcnt vmcnt(0)
	v_add_f32_e32 v128, v131, v128
	v_fmac_f32_e32 v129, 0x3a800000, v128
	v_mul_f32_e32 v128, 0x4f800000, v129
	v_cmp_gt_f32_e32 vcc, s0, v129
	v_mov_b32_e32 v131, 0x260
	s_nop 0
	v_cndmask_b32_e32 v128, v129, v128, vcc
	v_sqrt_f32_e32 v129, v128
	s_nop 0
	v_add_u32_e32 v132, -1, v129
	v_add_u32_e32 v133, 1, v129
	v_fma_f32 v134, -v132, v129, v128
	v_fma_f32 v135, -v133, v129, v128
	v_cmp_ge_f32_e64 s[0:1], 0, v134
	s_nop 1
	v_cndmask_b32_e64 v129, v129, v132, s[0:1]
	v_cmp_lt_f32_e64 s[0:1], 0, v135
	s_nop 1
	v_cndmask_b32_e64 v129, v129, v133, s[0:1]
	v_mul_f32_e32 v132, 0x37800000, v129
	v_cndmask_b32_e32 v129, v129, v132, vcc
	v_cmp_class_f32_e32 vcc, v128, v131
	s_nop 1
	v_cndmask_b32_e32 v128, v129, v128, vcc
	v_div_scale_f32 v129, s[0:1], v128, v128, 1.0
	v_rcp_f32_e32 v131, v129
	v_div_scale_f32 v132, vcc, 1.0, v128, 1.0
	v_fma_f32 v133, -v129, v131, 1.0
	v_fmac_f32_e32 v131, v133, v131
	v_mul_f32_e32 v133, v132, v131
	v_fma_f32 v134, -v129, v133, v132
	v_fmac_f32_e32 v133, v134, v131
	v_fma_f32 v129, -v129, v133, v132
	v_div_fmas_f32 v129, v129, v131, v133
	v_div_fixup_f32 v128, v129, v128, 1.0
	v_lshl_add_u32 v129, v130, 2, 0
	ds_write_b32 v129, v128 offset:4096
